# dense attention: K LDS swizzle over 16 rows (conflict-free b128 reads), j/half counters moved to free SGPRs
# baseline (speedup 1.0000x reference)
; __device__ __forceinline__ int TID() { int t = threadIdx.x; asm volatile("" : "+v"(t)); return t; }
; __device__ __forceinline__ int v_rd_base(int lane) { return ((lane & 3) << 3) | (((lane >> 2) & 3) << 6) | (((lane >> 4) & 1) << 5) | (((lane >> 5) & 1) << 8); }
; #define SWAIT() do { if constexpr (SDEPTH == 2) asm volatile("s_waitcnt vmcnt(4)" ::: "memory"); else asm volatile("s_waitcnt vmcnt(0)" ::: "memory"); } while (0)
; #define ROW0(t) tile_row0<MODE>(u, (t))
; template <int MODE, int SDEPTH>
; __device__ __forceinline__ void attn_unit(const UnitP& u, char* lds) {
;   const int tid = TID(), wid = tid >> 6, lane = tid & 63, r32 = lane & 31, hi = lane >> 5;
;   bf16_t* V_lds = (bf16_t*)lds; bf16_t* K_lds = (bf16_t*)(lds + 2 * SHM_V);
;   float* ws = (float*)(lds + 2 * SHM_V + 2 * SHM_K) + wid * 64; float* li_l = ws; float* al_l = ws + 32;
;   const float* biasL = (const float*)(lds + BIAS_OFF);
;   const bf16_t* __restrict__ Kh = u.K; const bf16_t* __restrict__ Vh = u.V; const int LDK = u.ldk;
;   float m_reg = -1e30f, l_reg = 0; f32x16 o[4] = {}; bf16x8 qr[8];
;   const bf16_t* Qw = u.Q + (long)(wid * QBLK + r32) * u.ldq + hi * 8;
; #pragma unroll
;   for (int d0 = 0; d0 < 8; ++d0) qr[d0] = *reinterpret_cast<const bf16x8*>(Qw + d0 * 16);
;   const int vb0 = (int)(uintptr_t)V_lds + v_rd_base(lane);
;   struct { bf16x8 vs0, vs1, ks0, ks1; } sr_[SDEPTH];
;     ...
;   f32x16 pA0, pA1, pB0, pB1; float mnA, mnB, alA, alB; bf16x8 pa0, pa1, pa2, pa3; const int NT = u.NT;
;   constexpr int SE = 0, SO = SDEPTH - 1;
;   SLOAD(SE, ROW0(0)); asm volatile("s_waitcnt vmcnt(0)" ::: "memory"); SWRITE(0, SE); __syncthreads();
;   qkt(pA0, pA1, K_lds, qr, r32, hi); mask_tile<MODE>(pA0, pA1, u, 0, wid, r32, hi, biasL); partialSM(pA0, pA1, m_reg, mnA, alA);
;   SLOAD(SO, ROW0(1)); if constexpr (SDEPTH == 2) { if (2 < NT) SLOAD(SE, ROW0(2)); }
;   SWAIT(); SWRITE(1, SO); __syncthreads();
.LBB0_528:
	s_andn2_b64 vcc, exec, s[8:9]
	s_mov_b64 s[8:9], -1
	s_cbranch_vccnz .LBB0_524
	s_lshl_b32 s2, s12, 8
	s_and_b32 s29, s2, 0x1f00
	s_and_b32 s13, s12, 0xffffff80
	s_mul_i32 s2, s29, 0x1800
	s_add_u32 s10, s19, s2
	s_addc_u32 s11, s20, 0
	s_lshl_b32 s2, s12, 2
	s_and_b32 s2, s2, 0xffffff80
	s_ashr_i32 s3, s2, 31
	s_lshl_b64 s[8:9], s[2:3], 1
	s_add_u32 s2, s10, s8
	s_addc_u32 s3, s11, s9
	s_add_i32 s10, s13, 0x800
	s_ashr_i32 s11, s10, 31
	s_lshl_b64 s[10:11], s[10:11], 1
	s_add_u32 s14, s19, s10
	s_addc_u32 s15, s20, s11
	s_add_i32 s12, s13, 0xa00
	s_ashr_i32 s13, s12, 31
	s_lshl_b64 s[12:13], s[12:13], 1
	v_mov_b32_e32 v48, v216
	s_add_u32 s16, s19, s12
	s_addc_u32 s17, s20, s13
	v_ashrrev_i32_e32 v195, 6, v48
	v_and_b32_e32 v193, 31, v48
	v_and_b32_e32 v0, 0x3fffffc0, v48
	s_add_i32 s34, 0, 0x10000
	v_lshlrev_b32_e32 v98, 5, v195
	v_bfe_u32 v194, v48, 5, 1
	v_lshl_add_u32 v99, v0, 2, s34
	v_or_b32_e32 v2, v98, v193
	v_mov_b64_e32 v[0:1], s[2:3]
	s_movk_i32 s36, 0x1800
	v_mad_i64_i32 v[0:1], s[2:3], v2, s36, v[0:1]
	v_lshlrev_b32_e32 v96, 4, v194
	v_and_b32_e32 v101, 63, v48
	v_lshl_add_u64 v[0:1], v[0:1], 0, v[96:97]
	v_lshlrev_b32_e32 v192, 4, v48
	global_load_dwordx4 v[130:133], v[0:1], off
	global_load_dwordx4 v[126:129], v[0:1], off offset:32
	global_load_dwordx4 v[122:125], v[0:1], off offset:64
	global_load_dwordx4 v[118:121], v[0:1], off offset:96
	global_load_dwordx4 v[114:117], v[0:1], off offset:128
	global_load_dwordx4 v[110:113], v[0:1], off offset:160
	global_load_dwordx4 v[106:109], v[0:1], off offset:192
	global_load_dwordx4 v[102:105], v[0:1], off offset:224
	v_lshlrev_b32_e32 v99, 8, v195
	v_add_u32_e32 v99, 0x22000, v99
	v_lshl_add_u32 v199, v193, 2, v99
	v_cmp_gt_u32_e64 s[40:41], 32, v101
	v_lshlrev_b32_e32 v0, 3, v101
	v_and_b32_e32 v1, 0xc0, v192
	v_lshlrev_b32_e32 v2, 1, v48
	v_and_or_b32 v1, v0, 24, v1
	v_and_b32_e32 v2, 32, v2
	v_and_b32_e32 v0, 0x100, v0
	v_or3_b32 v196, v1, v2, v0
	v_ashrrev_i32_e32 v50, 4, v48
	v_lshlrev_b32_e32 v16, 3, v48
	v_and_b32_e32 v51, 0x78, v16
	v_and_b32_e32 v3, 15, v48
	v_lshlrev_b32_e32 v3, 4, v3
	v_mov_b32_e32 v5, 0
	s_movk_i32 s2, 0x1800
	v_mad_u32_u24 v4, v50, s2, v3
	v_lshl_add_u64 v[188:189], s[16:17], 0, v[4:5]
	v_lshl_add_u64 v[184:185], s[14:15], 0, v[4:5]
	s_mov_b64 s[2:3], 0x30000
	v_lshl_add_u64 v[190:191], v[188:189], 0, s[2:3]
	v_lshl_add_u64 v[186:187], v[184:185], 0, s[2:3]
	s_mov_b64 s[2:3], 0x60000
	global_load_dwordx4 v[134:137], v[188:189], off
	global_load_dwordx4 v[138:141], v[190:191], off
	global_load_dwordx4 v[142:145], v[184:185], off
	global_load_dwordx4 v[146:149], v[186:187], off
	v_lshl_add_u64 v[184:185], v[184:185], 0, s[2:3]
	v_lshl_add_u64 v[186:187], v[186:187], 0, s[2:3]
	v_lshl_add_u64 v[188:189], v[188:189], 0, s[2:3]
	v_lshl_add_u64 v[190:191], v[190:191], 0, s[2:3]
	global_load_dwordx4 v[150:153], v[188:189], off
	global_load_dwordx4 v[154:157], v[190:191], off
	global_load_dwordx4 v[158:161], v[184:185], off
	global_load_dwordx4 v[162:165], v[186:187], off
	v_lshl_add_u64 v[184:185], v[184:185], 0, s[2:3]
	v_lshl_add_u64 v[186:187], v[186:187], 0, s[2:3]
	v_lshl_add_u64 v[188:189], v[188:189], 0, s[2:3]
	v_lshl_add_u64 v[190:191], v[190:191], 0, s[2:3]
	v_and_b32_e32 v18, 0xfffff0, v50
	v_lshlrev_b32_e32 v19, 1, v50
	v_and_or_b32 v18, v19, 8, v18
	v_lshrrev_b32_e32 v19, 1, v50
	v_lshrrev_b32_e32 v18, 1, v18
	v_bfe_u32 v16, v16, 5, 2
	v_and_b32_e32 v20, 3, v50
	v_or_b32_e32 v18, v18, v16
	v_and_or_b32 v19, v19, 4, v20
	v_lshlrev_b32_e32 v20, 1, v51
	v_lshlrev_b32_e32 v18, 9, v18
	v_lshlrev_b32_e32 v19, 6, v19
	v_and_b32_e32 v21, 48, v20
	v_or3_b32 v197, v18, v19, v21
	v_lshlrev_b32_e32 v4, 8, v50
	v_and_b32_e32 v5, 0xf0, v48
	v_bitop3_b32 v4, v20, v4, v5 bitop3:0xde
	v_add_u32_e32 v200, 0x10000, v4
	v_lshlrev_b32_e32 v60, 8, v193
	v_and_b32_e32 v61, 0xf0, v192
	v_bitop3_b32 v52, v96, v60, v61 bitop3:0xde
	v_add_u32_e32 v204, 0x10000, v52
	v_or_b32_e32 v52, 32, v96
	v_bitop3_b32 v52, v52, v60, v61 bitop3:0xde
	v_add_u32_e32 v205, 0x10000, v52
	v_or_b32_e32 v52, 64, v96
	v_bitop3_b32 v52, v52, v60, v61 bitop3:0xde
	v_add_u32_e32 v206, 0x10000, v52
	v_or_b32_e32 v52, 96, v96
	v_bitop3_b32 v52, v52, v60, v61 bitop3:0xde
	v_add_u32_e32 v207, 0x10000, v52
	v_or_b32_e32 v52, 128, v96
	v_bitop3_b32 v52, v52, v60, v61 bitop3:0xde
	v_add_u32_e32 v208, 0x10000, v52
	v_or_b32_e32 v52, 160, v96
	v_bitop3_b32 v52, v52, v60, v61 bitop3:0xde
	v_add_u32_e32 v209, 0x10000, v52
	v_or_b32_e32 v52, 192, v96
	v_bitop3_b32 v52, v52, v60, v61 bitop3:0xde
	v_add_u32_e32 v210, 0x10000, v52
	v_or_b32_e32 v52, 224, v96
	v_bitop3_b32 v52, v52, v60, v61 bitop3:0xde
	v_add_u32_e32 v211, 0x10000, v52
	v_mov_b32_e32 v174, v224
	v_mov_b32_e32 v175, 0
	s_mov_b32 s31, 0
	v_readfirstlane_b32 s36, v195
	s_waitcnt vmcnt(4)
	ds_write_b128 v197, v[134:137] offset:0
	ds_write_b128 v197, v[138:141] offset:8192
	ds_write_b128 v200, v[142:145] offset:0
	ds_write_b128 v200, v[146:149] offset:8192
	s_waitcnt vmcnt(0)
	ds_write_b128 v197, v[150:153] offset:16384
	ds_write_b128 v197, v[154:157] offset:24576
	ds_write_b128 v200, v[158:161] offset:16384
	ds_write_b128 v200, v[162:165] offset:24576
	s_nop 1
	global_load_dwordx4 v[134:137], v[188:189], off
	global_load_dwordx4 v[138:141], v[190:191], off
	global_load_dwordx4 v[142:145], v[184:185], off
	global_load_dwordx4 v[146:149], v[186:187], off
	v_lshl_add_u64 v[184:185], v[184:185], 0, s[2:3]
	v_lshl_add_u64 v[186:187], v[186:187], 0, s[2:3]
	v_lshl_add_u64 v[188:189], v[188:189], 0, s[2:3]
	v_lshl_add_u64 v[190:191], v[190:191], 0, s[2:3]
	v_mov_b32_e32 v0, 0
	v_mov_b32_e32 v1, 0
	v_mov_b32_e32 v2, 0
	v_mov_b32_e32 v3, 0
	v_mov_b32_e32 v4, 0
	v_mov_b32_e32 v5, 0
	v_mov_b32_e32 v6, 0
	v_mov_b32_e32 v7, 0
	v_mov_b32_e32 v8, 0
	v_mov_b32_e32 v9, 0
	v_mov_b32_e32 v10, 0
	v_mov_b32_e32 v11, 0
	v_mov_b32_e32 v12, 0
	v_mov_b32_e32 v13, 0
	v_mov_b32_e32 v14, 0
	v_mov_b32_e32 v15, 0
	v_mov_b32_e32 v48, 0
	v_mov_b32_e32 v49, 0
	v_mov_b32_e32 v50, 0
	v_mov_b32_e32 v51, 0
	v_mov_b32_e32 v52, 0
	v_mov_b32_e32 v53, 0
	v_mov_b32_e32 v54, 0
	v_mov_b32_e32 v55, 0
	v_mov_b32_e32 v56, 0
	v_mov_b32_e32 v57, 0
	v_mov_b32_e32 v58, 0
	v_mov_b32_e32 v59, 0
	v_mov_b32_e32 v60, 0
	v_mov_b32_e32 v61, 0
	v_mov_b32_e32 v62, 0
	v_mov_b32_e32 v63, 0
	v_mov_b32_e32 v32, 0
	v_mov_b32_e32 v33, 0
	v_mov_b32_e32 v34, 0
	v_mov_b32_e32 v35, 0
	v_mov_b32_e32 v36, 0
	v_mov_b32_e32 v37, 0
	v_mov_b32_e32 v38, 0
	v_mov_b32_e32 v39, 0
	v_mov_b32_e32 v40, 0
	v_mov_b32_e32 v41, 0
	v_mov_b32_e32 v42, 0
	v_mov_b32_e32 v43, 0
	v_mov_b32_e32 v44, 0
	v_mov_b32_e32 v45, 0
	v_mov_b32_e32 v46, 0
	v_mov_b32_e32 v47, 0
	v_mov_b32_e32 v16, 0
	v_mov_b32_e32 v17, 0
	v_mov_b32_e32 v18, 0
	v_mov_b32_e32 v19, 0
	v_mov_b32_e32 v20, 0
	v_mov_b32_e32 v21, 0
	v_mov_b32_e32 v22, 0
	v_mov_b32_e32 v23, 0
	v_mov_b32_e32 v24, 0
	v_mov_b32_e32 v25, 0
	v_mov_b32_e32 v26, 0
	v_mov_b32_e32 v27, 0
	v_mov_b32_e32 v28, 0
	v_mov_b32_e32 v29, 0
	v_mov_b32_e32 v30, 0
	v_mov_b32_e32 v31, 0
	s_waitcnt lgkmcnt(0)
	s_barrier
; __device__ __forceinline__ void qkt(f32x16& p0, f32x16& p1, const bf16_t* Ks, const bf16x8* qr, int r32, int hi) {
;   p0 = f32x16{}; p1 = f32x16{};
; #pragma unroll
;   for (int d0 = 0; d0 < 8; ++d0) { int cb = (d0 * 16 + hi * 8) * 2;
;     bf16x8 b0 = *reinterpret_cast<const bf16x8*>((const char*)Ks + KSWZ(r32, cb));
;     bf16x8 b1 = *reinterpret_cast<const bf16x8*>((const char*)Ks + KSWZ(32 + r32, cb));
	ds_read_b128 v[150:153], v204 offset:0
	ds_read_b128 v[154:157], v204 offset:8192
	ds_read_b128 v[158:161], v205 offset:0
	ds_read_b128 v[162:165], v205 offset:8192
	ds_read_b128 v[228:231], v206 offset:0
	ds_read_b128 v[232:235], v206 offset:8192
	ds_read_b128 v[236:239], v207 offset:0
	ds_read_b128 v[240:243], v207 offset:8192
	s_cmp_lt_u32 s36, 4
	s_cbranch_scc1 .Lda_lead
	s_barrier

; __device__ __forceinline__ void partialSM(f32x16& p0, f32x16& p1, float& m_reg, float& mn, float& alpha) {
;   constexpr float C = SCALE * 1.4426950408889634f;
;   float pmax = p0[0];
; #pragma unroll
;   for (int r = 1; r < 16; ++r) pmax = fmaxf(pmax, p0[r]);
; #pragma unroll
;   for (int r = 0; r < 16; ++r) pmax = fmaxf(pmax, p1[r]);
;   { auto rr = __builtin_amdgcn_permlane32_swap(__float_as_uint(pmax), __float_as_uint(pmax), false, false);
;     pmax = fmaxf(__uint_as_float(rr[0]), __uint_as_float(rr[1])); }
;   if (__builtin_expect(__all(pmax - m_reg <= THR / SCALE), 1)) { mn = m_reg; alpha = 1.f; }
;   else { mn = fmaxf(m_reg, pmax); alpha = __builtin_amdgcn_exp2f((m_reg - mn) * C); m_reg = mn; }
;   float mnC = -mn * C;
; #pragma unroll
;   for (int r = 0; r < 16; ++r) p0[r] = fmaf(p0[r], C, mnC);
; #pragma unroll
;   for (int r = 0; r < 16; ++r) p1[r] = fmaf(p1[r], C, mnC);
; #pragma unroll
;   for (int r = 0; r < 16; ++r) p0[r] = __builtin_amdgcn_exp2f(p0[r]);
; }
; __device__ __forceinline__ void finishSM(f32x16& p0, f32x16& p1, float alpha, float& l_reg, bf16x8& pa0, bf16x8& pa1, bf16x8& pa2, bf16x8& pa3) {
; #pragma unroll
;   for (int r = 0; r < 16; ++r) p1[r] = __builtin_amdgcn_exp2f(p1[r]);
;   float ps = 0;
; #pragma unroll
;   for (int r = 0; r < 16; ++r) ps += p0[r];
; #pragma unroll
;   for (int r = 0; r < 16; ++r) ps += p1[r];
;   { auto rr = __builtin_amdgcn_permlane32_swap(__float_as_uint(ps), __float_as_uint(ps), false, false);
;     ps = __uint_as_float(rr[0]) + __uint_as_float(rr[1]); }
;   l_reg = l_reg * alpha + ps;
;     ...
;   PK4(p0, 0, pa0); PK4(p0, 8, pa1); PK4(p1, 0, pa2); PK4(p1, 8, pa3);
;     ...
; }
.Lda_y0:
	s_barrier
	v_max3_f32 v201, v80, v81, v82
	v_max3_f32 v202, v64, v65, v66
	v_max3_f32 v201, v201, v83, v84
	v_max3_f32 v202, v202, v67, v68
	v_max3_f32 v201, v201, v85, v86
	v_max3_f32 v202, v202, v69, v70
	v_max3_f32 v201, v201, v87, v88
	v_max3_f32 v202, v202, v71, v72
	v_max3_f32 v201, v201, v89, v90
	v_max3_f32 v202, v202, v73, v74
	v_max3_f32 v201, v201, v91, v92
	v_max3_f32 v202, v202, v75, v76
	v_max3_f32 v201, v201, v93, v94
	v_max3_f32 v202, v202, v77, v78
	v_max3_f32 v201, v201, v95, v79
	v_max_f32_e32 v201, v201, v202
	v_mov_b32_e32 v202, v201
	s_nop 1
	v_permlane32_swap_b32_e32 v201, v202
	s_nop 0
	v_max_f32_e32 v212, v201, v202
	v_sub_f32_e32 v201, v212, v174
	v_cmp_ge_f32_e32 vcc, s86, v201
	v_max_f32_e32 v202, v174, v212
	v_sub_f32_e32 v215, v174, v202
	v_mul_f32_e32 v215, s92, v215
	s_nop 1
	s_cmp_eq_u64 vcc, exec
	s_cselect_b64 s[42:43], -1, 0
	v_exp_f32_e32 v213, v215
	s_nop 0
	v_cndmask_b32_e64 v174, v202, v174, s[42:43]
	v_cndmask_b32_e64 v213, v213, 1.0, s[42:43]
	v_mul_f32_e32 v214, 0xbe0293ee, v174
	s_nop 0
	v_cmp_gt_f32_e32 vcc, 1.0, v213
	v_fma_f32 v80, v80, s92, v214
	v_fma_f32 v81, v81, s92, v214
	v_fma_f32 v82, v82, s92, v214
	v_fma_f32 v83, v83, s92, v214
	v_fma_f32 v84, v84, s92, v214
	v_fma_f32 v85, v85, s92, v214
	v_fma_f32 v86, v86, s92, v214
	v_fma_f32 v87, v87, s92, v214
	v_fma_f32 v88, v88, s92, v214
	v_fma_f32 v89, v89, s92, v214
	v_fma_f32 v90, v90, s92, v214
	v_fma_f32 v91, v91, s92, v214
	v_fma_f32 v92, v92, s92, v214
	v_fma_f32 v93, v93, s92, v214
	v_fma_f32 v94, v94, s92, v214
	v_fma_f32 v95, v95, s92, v214
	v_fma_f32 v64, v64, s92, v214
	v_fma_f32 v65, v65, s92, v214
	v_fma_f32 v66, v66, s92, v214
	v_fma_f32 v67, v67, s92, v214
	v_fma_f32 v68, v68, s92, v214
	v_fma_f32 v69, v69, s92, v214
	v_fma_f32 v70, v70, s92, v214
	v_fma_f32 v71, v71, s92, v214
	v_fma_f32 v72, v72, s92, v214
	v_fma_f32 v73, v73, s92, v214
	v_fma_f32 v74, v74, s92, v214
	v_fma_f32 v75, v75, s92, v214
	v_fma_f32 v76, v76, s92, v214
	v_fma_f32 v77, v77, s92, v214
	v_fma_f32 v78, v78, s92, v214
	v_fma_f32 v79, v79, s92, v214
	s_cbranch_vccz .Lda_noresc_0
	s_and_saveexec_b64 s[12:13], s[40:41]
	ds_write_b32 v199, v213 offset:128
	s_or_b64 exec, exec, s[12:13]
	s_waitcnt lgkmcnt(0)
	v_add_u32_e32 v215, v99, v96
	ds_read_b128 v[228:231], v215 offset:128
	ds_read_b128 v[232:235], v215 offset:160
	ds_read_b128 v[236:239], v215 offset:192
	ds_read_b128 v[240:243], v215 offset:224
	s_waitcnt lgkmcnt(0)
	v_pk_mul_f32 v[0:1], v[0:1], v[228:229]
	v_pk_mul_f32 v[2:3], v[2:3], v[230:231]
	v_pk_mul_f32 v[4:5], v[4:5], v[232:233]
	v_pk_mul_f32 v[6:7], v[6:7], v[234:235]
	v_pk_mul_f32 v[8:9], v[8:9], v[236:237]
	v_pk_mul_f32 v[10:11], v[10:11], v[238:239]
	v_pk_mul_f32 v[12:13], v[12:13], v[240:241]
	v_pk_mul_f32 v[14:15], v[14:15], v[242:243]
	v_pk_mul_f32 v[48:49], v[48:49], v[228:229]
	v_pk_mul_f32 v[50:51], v[50:51], v[230:231]
	v_pk_mul_f32 v[52:53], v[52:53], v[232:233]
	v_pk_mul_f32 v[54:55], v[54:55], v[234:235]
	v_pk_mul_f32 v[56:57], v[56:57], v[236:237]
	v_pk_mul_f32 v[58:59], v[58:59], v[238:239]
	v_pk_mul_f32 v[60:61], v[60:61], v[240:241]
	v_pk_mul_f32 v[62:63], v[62:63], v[242:243]
	v_pk_mul_f32 v[32:33], v[32:33], v[228:229]
	v_pk_mul_f32 v[34:35], v[34:35], v[230:231]
	v_pk_mul_f32 v[36:37], v[36:37], v[232:233]
	v_pk_mul_f32 v[38:39], v[38:39], v[234:235]
	v_pk_mul_f32 v[40:41], v[40:41], v[236:237]
	v_pk_mul_f32 v[42:43], v[42:43], v[238:239]
	v_pk_mul_f32 v[44:45], v[44:45], v[240:241]
	v_pk_mul_f32 v[46:47], v[46:47], v[242:243]
	v_pk_mul_f32 v[16:17], v[16:17], v[228:229]
	v_pk_mul_f32 v[18:19], v[18:19], v[230:231]
	v_pk_mul_f32 v[20:21], v[20:21], v[232:233]
	v_pk_mul_f32 v[22:23], v[22:23], v[234:235]
	v_pk_mul_f32 v[24:25], v[24:25], v[236:237]
	v_pk_mul_f32 v[26:27], v[26:27], v[238:239]
	v_pk_mul_f32 v[28:29], v[28:29], v[240:241]
	v_pk_mul_f32 v[30:31], v[30:31], v[242:243]
.Lda_noresc_0:
	v_exp_f32_e32 v80, v80
	v_exp_f32_e32 v81, v81
	v_exp_f32_e32 v82, v82
	v_exp_f32_e32 v83, v83
	v_exp_f32_e32 v84, v84
	v_exp_f32_e32 v85, v85
	v_exp_f32_e32 v86, v86
	v_exp_f32_e32 v87, v87
	v_exp_f32_e32 v88, v88
	v_exp_f32_e32 v89, v89
	v_exp_f32_e32 v90, v90
	v_exp_f32_e32 v91, v91
	v_exp_f32_e32 v92, v92
	v_exp_f32_e32 v93, v93
	v_exp_f32_e32 v94, v94
	v_exp_f32_e32 v95, v95
	v_exp_f32_e32 v64, v64
	v_exp_f32_e32 v65, v65
	v_exp_f32_e32 v66, v66
	v_exp_f32_e32 v67, v67
	v_exp_f32_e32 v68, v68
	v_exp_f32_e32 v69, v69
	v_exp_f32_e32 v70, v70
	v_exp_f32_e32 v71, v71
	v_exp_f32_e32 v72, v72
	v_exp_f32_e32 v73, v73
	v_exp_f32_e32 v74, v74
	v_exp_f32_e32 v75, v75
	v_exp_f32_e32 v76, v76
	v_exp_f32_e32 v77, v77
	v_exp_f32_e32 v78, v78
	v_exp_f32_e32 v79, v79
	v_add_f32_e32 v201, v80, v81
	v_add_f32_e32 v202, v82, v83
	v_add_f32_e32 v201, v201, v84
	v_add_f32_e32 v202, v202, v85
	v_add_f32_e32 v201, v201, v86
	v_add_f32_e32 v202, v202, v87
	v_add_f32_e32 v201, v201, v88
	v_add_f32_e32 v202, v202, v89
	v_add_f32_e32 v201, v201, v90
	v_add_f32_e32 v202, v202, v91
	v_add_f32_e32 v201, v201, v92
	v_add_f32_e32 v202, v202, v93
	v_add_f32_e32 v201, v201, v94
	v_add_f32_e32 v202, v202, v95
	v_add_f32_e32 v201, v201, v64
	v_add_f32_e32 v202, v202, v65
	v_add_f32_e32 v201, v201, v66
	v_add_f32_e32 v202, v202, v67
	v_add_f32_e32 v201, v201, v68
	v_add_f32_e32 v202, v202, v69
	v_add_f32_e32 v201, v201, v70
	v_add_f32_e32 v202, v202, v71
	v_add_f32_e32 v201, v201, v72
	v_add_f32_e32 v202, v202, v73
	v_add_f32_e32 v201, v201, v74
	v_add_f32_e32 v202, v202, v75
	v_add_f32_e32 v201, v201, v76
	v_add_f32_e32 v202, v202, v77
	v_add_f32_e32 v201, v201, v78
	v_add_f32_e32 v202, v202, v79
	v_add_f32_e32 v201, v201, v202
	v_mov_b32_e32 v202, v201
	v_cvt_pk_bf16_f32 v166, v80, v81
	v_cvt_pk_bf16_f32 v167, v82, v83
	v_cvt_pk_bf16_f32 v168, v84, v85
	v_cvt_pk_bf16_f32 v169, v86, v87
	v_cvt_pk_bf16_f32 v170, v88, v89
	v_cvt_pk_bf16_f32 v171, v90, v91
	v_cvt_pk_bf16_f32 v172, v92, v93
	v_cvt_pk_bf16_f32 v173, v94, v95
	v_cvt_pk_bf16_f32 v176, v64, v65
	v_cvt_pk_bf16_f32 v177, v66, v67
	v_cvt_pk_bf16_f32 v178, v68, v69
	v_cvt_pk_bf16_f32 v179, v70, v71
	v_cvt_pk_bf16_f32 v180, v72, v73
	v_cvt_pk_bf16_f32 v181, v74, v75
	v_cvt_pk_bf16_f32 v182, v76, v77
	v_cvt_pk_bf16_f32 v183, v78, v79
	s_nop 1
	v_permlane32_swap_b32_e32 v201, v202
	v_permlane32_swap_b32_e32 v166, v168
	v_permlane32_swap_b32_e32 v167, v169
	v_permlane32_swap_b32_e32 v170, v172
	v_permlane32_swap_b32_e32 v171, v173
	v_permlane32_swap_b32_e32 v176, v178
	v_permlane32_swap_b32_e32 v177, v179
	v_permlane32_swap_b32_e32 v180, v182
	v_permlane32_swap_b32_e32 v181, v183
	v_add_f32_e32 v201, v201, v202
	v_fma_f32 v175, v175, v213, v201
	s_cmp_lt_u32 s31, 130
	s_cbranch_scc0 .Lda_skipw_0
	s_waitcnt vmcnt(0)
	ds_write_b128 v197, v[134:137] offset:32768
	ds_write_b128 v197, v[138:141] offset:40960
	ds_write_b128 v200, v[142:145] offset:32768
	ds_write_b128 v200, v[146:149] offset:40960
	s_nop 1
; #define SBAR() __builtin_amdgcn_sched_barrier(0)
; __device__ __forceinline__ void qkt(f32x16& p0, f32x16& p1, const bf16_t* Ks, const bf16x8* qr, int r32, int hi) {
;   p0 = f32x16{}; p1 = f32x16{};
; #pragma unroll
;   for (int d0 = 0; d0 < 8; ++d0) { int cb = (d0 * 16 + hi * 8) * 2;
;     bf16x8 b0 = *reinterpret_cast<const bf16x8*>((const char*)Ks + KSWZ(r32, cb));
;     bf16x8 b1 = *reinterpret_cast<const bf16x8*>((const char*)Ks + KSWZ(32 + r32, cb));
;     p0 = __builtin_amdgcn_mfma_f32_32x32x16_bf16(b0, qr[d0], p0, 0, 0, 0);
;     p1 = __builtin_amdgcn_mfma_f32_32x32x16_bf16(b1, qr[d0], p1, 0, 0, 0); }
; }
; __device__ __forceinline__ int v_st(int k, int c) { const int kk = (k & ~0xC) | ((k & 4) << 1) | ((k & 8) >> 1); return ((kk >> 3) * 4 + (c >> 5)) * 512 + ((kk & 7) * 32 + (c & 31)) * 2; }
; __device__ __forceinline__ int v_rd_base(int lane) { return ((lane & 3) << 3) | (((lane >> 2) & 3) << 6) | (((lane >> 4) & 1) << 5) | (((lane >> 5) & 1) << 8); }
; template <int OFF> __device__ __forceinline__ s16x4 tr_read(int vb) {
;   s16x4 r; asm volatile("ds_read_b64_tr_b16 %0, %1 offset:%2" : "=&v"(r) : "v"(vb), "i"(OFF) : "memory"); return r;
; }
; template <int D0> __device__ __forceinline__ void pv_one(f32x16& od, int vb, bf16x8 pa0, bf16x8 pa1, bf16x8 pa2, bf16x8 pa3) {
;   const s16x4 l0 = tr_read<v_rd_off(D0, 0, 0)>(vb), h0 = tr_read<v_rd_off(D0, 0, 1)>(vb), l1 = tr_read<v_rd_off(D0, 1, 0)>(vb), h1 = tr_read<v_rd_off(D0, 1, 1)>(vb);
;   const s16x4 l2 = tr_read<v_rd_off(D0, 2, 0)>(vb), h2 = tr_read<v_rd_off(D0, 2, 1)>(vb), l3 = tr_read<v_rd_off(D0, 3, 0)>(vb), h3 = tr_read<v_rd_off(D0, 3, 1)>(vb);
;   asm volatile("s_waitcnt lgkmcnt(0)" ::: "memory"); SBAR();
;     ...
;   od = __builtin_amdgcn_mfma_f32_32x32x16_bf16(pa0, PK(l0, h0), od, 0, 0, 0);
;   od = __builtin_amdgcn_mfma_f32_32x32x16_bf16(pa1, PK(l1, h1), od, 0, 0, 0);
;   od = __builtin_amdgcn_mfma_f32_32x32x16_bf16(pa2, PK(l2, h2), od, 0, 0, 0);
;   od = __builtin_amdgcn_mfma_f32_32x32x16_bf16(pa3, PK(l3, h3), od, 0, 0, 0);
;     ...
; }
; __device__ __forceinline__ void pv_d0(f32x16* o, int vb, bf16x8 pa0, bf16x8 pa1, bf16x8 pa2, bf16x8 pa3) {
;   pv_one<0>(o[0], vb, pa0, pa1, pa2, pa3); pv_one<1>(o[1], vb, pa0, pa1, pa2, pa3); pv_one<2>(o[2], vb, pa0, pa1, pa2, pa3); pv_one<3>(o[3], vb, pa0, pa1, pa2, pa3);
.Lda_skipw_0:
	s_cmp_lt_u32 s31, 129
	s_cbranch_scc0 .Lda_skipl_0
	global_load_dwordx4 v[134:137], v[188:189], off
	global_load_dwordx4 v[138:141], v[190:191], off
	global_load_dwordx4 v[142:145], v[184:185], off
	global_load_dwordx4 v[146:149], v[186:187], off
	v_lshl_add_u64 v[184:185], v[184:185], 0, s[2:3]
	v_lshl_add_u64 v[186:187], v[186:187], 0, s[2:3]
	v_lshl_add_u64 v[188:189], v[188:189], 0, s[2:3]
	v_lshl_add_u64 v[190:191], v[190:191], 0, s[2:3]
.Lda_skipl_0:
	s_add_u32 s31, s31, 1
	s_cmp_lt_u32 s31, 132
	s_cbranch_scc0 .Lda_skipk_0
	ds_read_b128 v[150:153], v204 offset:16384
	ds_read_b128 v[154:157], v204 offset:24576
	ds_read_b128 v[158:161], v205 offset:16384
	ds_read_b128 v[162:165], v205 offset:24576
	ds_read_b128 v[228:231], v206 offset:16384
	ds_read_b128 v[232:235], v206 offset:24576
	ds_read_b128 v[236:239], v207 offset:16384
	ds_read_b128 v[240:243], v207 offset:24576
.Lda_skipk_0:
	s_barrier
	s_waitcnt lgkmcnt(6)
	v_mfma_f32_32x32x16_bf16 v[80:95], v[150:153], v[130:133], 0
	v_mfma_f32_32x32x16_bf16 v[64:79], v[154:157], v[130:133], 0
	ds_read_b128 v[150:153], v208 offset:16384
	ds_read_b128 v[154:157], v208 offset:24576
	s_waitcnt lgkmcnt(6)
	v_mfma_f32_32x32x16_bf16 v[80:95], v[158:161], v[126:129], v[80:95]
	v_mfma_f32_32x32x16_bf16 v[64:79], v[162:165], v[126:129], v[64:79]
	ds_read_b128 v[158:161], v209 offset:16384
	ds_read_b128 v[162:165], v209 offset:24576
	s_waitcnt lgkmcnt(6)
	v_mfma_f32_32x32x16_bf16 v[80:95], v[228:231], v[122:125], v[80:95]
	v_mfma_f32_32x32x16_bf16 v[64:79], v[232:235], v[122:125], v[64:79]
	ds_read_b128 v[228:231], v210 offset:16384
	ds_read_b128 v[232:235], v210 offset:24576
	s_waitcnt lgkmcnt(6)
	v_mfma_f32_32x32x16_bf16 v[80:95], v[236:239], v[118:121], v[80:95]
	v_mfma_f32_32x32x16_bf16 v[64:79], v[240:243], v[118:121], v[64:79]
	ds_read_b128 v[236:239], v211 offset:16384
	ds_read_b128 v[240:243], v211 offset:24576
	s_waitcnt lgkmcnt(6)
	v_mfma_f32_32x32x16_bf16 v[80:95], v[150:153], v[114:117], v[80:95]
	v_mfma_f32_32x32x16_bf16 v[64:79], v[154:157], v[114:117], v[64:79]
	ds_read_b64_tr_b16 v[150:151], v196 offset:0
	ds_read_b64_tr_b16 v[152:153], v196 offset:2048
	ds_read_b64_tr_b16 v[154:155], v196 offset:4096
	ds_read_b64_tr_b16 v[156:157], v196 offset:6144
	s_waitcnt lgkmcnt(8)
	v_mfma_f32_32x32x16_bf16 v[80:95], v[158:161], v[110:113], v[80:95]
	v_mfma_f32_32x32x16_bf16 v[64:79], v[162:165], v[110:113], v[64:79]
	ds_read_b64_tr_b16 v[158:159], v196 offset:8192
	ds_read_b64_tr_b16 v[160:161], v196 offset:10240
	ds_read_b64_tr_b16 v[162:163], v196 offset:12288
	ds_read_b64_tr_b16 v[164:165], v196 offset:14336
	s_waitcnt lgkmcnt(10)
	v_mfma_f32_32x32x16_bf16 v[80:95], v[228:231], v[106:109], v[80:95]
	v_mfma_f32_32x32x16_bf16 v[64:79], v[232:235], v[106:109], v[64:79]
	ds_read_b64_tr_b16 v[228:229], v196 offset:512
	ds_read_b64_tr_b16 v[230:231], v196 offset:2560
	ds_read_b64_tr_b16 v[232:233], v196 offset:4608
	ds_read_b64_tr_b16 v[234:235], v196 offset:6656
	s_waitcnt lgkmcnt(12)
	v_mfma_f32_32x32x16_bf16 v[80:95], v[236:239], v[102:105], v[80:95]
	v_mfma_f32_32x32x16_bf16 v[64:79], v[240:243], v[102:105], v[64:79]
	ds_read_b64_tr_b16 v[236:237], v196 offset:8704
	ds_read_b64_tr_b16 v[238:239], v196 offset:10752
	s_waitcnt lgkmcnt(12)
	v_mfma_f32_32x32x16_bf16 v[0:15], v[166:169], v[150:153], v[0:15]
	ds_read_b64_tr_b16 v[240:241], v196 offset:12800
	ds_read_b64_tr_b16 v[242:243], v196 offset:14848
	s_waitcnt lgkmcnt(12)
	v_mfma_f32_32x32x16_bf16 v[0:15], v[170:173], v[154:157], v[0:15]
	ds_read_b64_tr_b16 v[150:151], v196 offset:1024
	ds_read_b64_tr_b16 v[152:153], v196 offset:3072
	s_waitcnt lgkmcnt(12)
	v_mfma_f32_32x32x16_bf16 v[0:15], v[176:179], v[158:161], v[0:15]
	ds_read_b64_tr_b16 v[154:155], v196 offset:5120
	ds_read_b64_tr_b16 v[156:157], v196 offset:7168
	s_waitcnt lgkmcnt(12)
	v_mfma_f32_32x32x16_bf16 v[0:15], v[180:183], v[162:165], v[0:15]
	ds_read_b64_tr_b16 v[158:159], v196 offset:9216
	ds_read_b64_tr_b16 v[160:161], v196 offset:11264
	s_waitcnt lgkmcnt(12)
	v_mfma_f32_32x32x16_bf16 v[48:63], v[166:169], v[228:231], v[48:63]
	ds_read_b64_tr_b16 v[162:163], v196 offset:13312
	ds_read_b64_tr_b16 v[164:165], v196 offset:15360
	s_waitcnt lgkmcnt(12)
	v_mfma_f32_32x32x16_bf16 v[48:63], v[170:173], v[232:235], v[48:63]
	ds_read_b64_tr_b16 v[228:229], v196 offset:1536
	ds_read_b64_tr_b16 v[230:231], v196 offset:3584
	s_waitcnt lgkmcnt(12)
	v_mfma_f32_32x32x16_bf16 v[48:63], v[176:179], v[236:239], v[48:63]
	ds_read_b64_tr_b16 v[232:233], v196 offset:5632
	ds_read_b64_tr_b16 v[234:235], v196 offset:7680
	s_waitcnt lgkmcnt(12)
	v_mfma_f32_32x32x16_bf16 v[48:63], v[180:183], v[240:243], v[48:63]
	ds_read_b64_tr_b16 v[236:237], v196 offset:9728
	ds_read_b64_tr_b16 v[238:239], v196 offset:11776
	s_waitcnt lgkmcnt(12)
	v_mfma_f32_32x32x16_bf16 v[32:47], v[166:169], v[150:153], v[32:47]
	ds_read_b64_tr_b16 v[240:241], v196 offset:13824
	ds_read_b64_tr_b16 v[242:243], v196 offset:15872
	s_waitcnt lgkmcnt(12)
	v_mfma_f32_32x32x16_bf16 v[32:47], v[170:173], v[154:157], v[32:47]
	s_waitcnt lgkmcnt(10)
	v_mfma_f32_32x32x16_bf16 v[32:47], v[176:179], v[158:161], v[32:47]
	s_waitcnt lgkmcnt(8)
	v_mfma_f32_32x32x16_bf16 v[32:47], v[180:183], v[162:165], v[32:47]
	s_waitcnt lgkmcnt(6)
	v_mfma_f32_32x32x16_bf16 v[16:31], v[166:169], v[228:231], v[16:31]
	s_waitcnt lgkmcnt(4)
	v_mfma_f32_32x32x16_bf16 v[16:31], v[170:173], v[232:235], v[16:31]
	s_waitcnt lgkmcnt(2)
	v_mfma_f32_32x32x16_bf16 v[16:31], v[176:179], v[236:239], v[16:31]
	s_waitcnt lgkmcnt(0)
	v_mfma_f32_32x32x16_bf16 v[16:31], v[180:183], v[240:243], v[16:31]
	s_barrier
; __device__ __forceinline__ void partialSM(f32x16& p0, f32x16& p1, float& m_reg, float& mn, float& alpha) {
;   constexpr float C = SCALE * 1.4426950408889634f;
;   float pmax = p0[0];
; #pragma unroll
;   for (int r = 1; r < 16; ++r) pmax = fmaxf(pmax, p0[r]);
; #pragma unroll
;   for (int r = 0; r < 16; ++r) pmax = fmaxf(pmax, p1[r]);
;   { auto rr = __builtin_amdgcn_permlane32_swap(__float_as_uint(pmax), __float_as_uint(pmax), false, false);
;     pmax = fmaxf(__uint_as_float(rr[0]), __uint_as_float(rr[1])); }
;   if (__builtin_expect(__all(pmax - m_reg <= THR / SCALE), 1)) { mn = m_reg; alpha = 1.f; }
;   else { mn = fmaxf(m_reg, pmax); alpha = __builtin_amdgcn_exp2f((m_reg - mn) * C); m_reg = mn; }
;   float mnC = -mn * C;
; #pragma unroll
;   for (int r = 0; r < 16; ++r) p0[r] = fmaf(p0[r], C, mnC);
; #pragma unroll
;   for (int r = 0; r < 16; ++r) p1[r] = fmaf(p1[r], C, mnC);
; #pragma unroll
;   for (int r = 0; r < 16; ++r) p0[r] = __builtin_amdgcn_exp2f(p0[r]);
; }
; __device__ __forceinline__ void finishSM(f32x16& p0, f32x16& p1, float alpha, float& l_reg, bf16x8& pa0, bf16x8& pa1, bf16x8& pa2, bf16x8& pa3) {
; #pragma unroll
;   for (int r = 0; r < 16; ++r) p1[r] = __builtin_amdgcn_exp2f(p1[r]);
;   float ps = 0;
; #pragma unroll
;   for (int r = 0; r < 16; ++r) ps += p0[r];
; #pragma unroll
;   for (int r = 0; r < 16; ++r) ps += p1[r];
;   { auto rr = __builtin_amdgcn_permlane32_swap(__float_as_uint(ps), __float_as_uint(ps), false, false);
;     ps = __uint_as_float(rr[0]) + __uint_as_float(rr[1]); }
;   l_reg = l_reg * alpha + ps;
;     ...
;   PK4(p0, 0, pa0); PK4(p0, 8, pa1); PK4(p1, 0, pa2); PK4(p1, 8, pa3);
;     ...
; }
	v_max3_f32 v201, v80, v81, v82
	v_max3_f32 v202, v64, v65, v66
	v_max3_f32 v201, v201, v83, v84
	v_max3_f32 v202, v202, v67, v68
	v_max3_f32 v201, v201, v85, v86
	v_max3_f32 v202, v202, v69, v70
	v_max3_f32 v201, v201, v87, v88
	v_max3_f32 v202, v202, v71, v72
	v_max3_f32 v201, v201, v89, v90
	v_max3_f32 v202, v202, v73, v74
	v_max3_f32 v201, v201, v91, v92
	v_max3_f32 v202, v202, v75, v76
	v_max3_f32 v201, v201, v93, v94
	v_max3_f32 v202, v202, v77, v78
	v_max3_f32 v201, v201, v95, v79
	v_max_f32_e32 v201, v201, v202
	v_mov_b32_e32 v202, v201
	s_nop 1
	v_permlane32_swap_b32_e32 v201, v202
	s_nop 0
	v_max_f32_e32 v212, v201, v202
	v_sub_f32_e32 v201, v212, v174
	v_cmp_ge_f32_e32 vcc, s86, v201
	v_max_f32_e32 v202, v174, v212
	v_sub_f32_e32 v215, v174, v202
	v_mul_f32_e32 v215, s92, v215
	s_nop 1
	s_cmp_eq_u64 vcc, exec
	s_cselect_b64 s[42:43], -1, 0
	v_exp_f32_e32 v213, v215
	s_nop 0
	v_cndmask_b32_e64 v174, v202, v174, s[42:43]
	v_cndmask_b32_e64 v213, v213, 1.0, s[42:43]
	v_mul_f32_e32 v214, 0xbe0293ee, v174
	s_nop 0
	v_cmp_gt_f32_e32 vcc, 1.0, v213
	v_fma_f32 v80, v80, s92, v214
	v_fma_f32 v81, v81, s92, v214
	v_fma_f32 v82, v82, s92, v214
	v_fma_f32 v83, v83, s92, v214
	v_fma_f32 v84, v84, s92, v214
	v_fma_f32 v85, v85, s92, v214
	v_fma_f32 v86, v86, s92, v214
	v_fma_f32 v87, v87, s92, v214
	v_fma_f32 v88, v88, s92, v214
	v_fma_f32 v89, v89, s92, v214
	v_fma_f32 v90, v90, s92, v214
	v_fma_f32 v91, v91, s92, v214
	v_fma_f32 v92, v92, s92, v214
	v_fma_f32 v93, v93, s92, v214
	v_fma_f32 v94, v94, s92, v214
	v_fma_f32 v95, v95, s92, v214
	v_fma_f32 v64, v64, s92, v214
	v_fma_f32 v65, v65, s92, v214
	v_fma_f32 v66, v66, s92, v214
	v_fma_f32 v67, v67, s92, v214
	v_fma_f32 v68, v68, s92, v214
	v_fma_f32 v69, v69, s92, v214
	v_fma_f32 v70, v70, s92, v214
	v_fma_f32 v71, v71, s92, v214
	v_fma_f32 v72, v72, s92, v214
	v_fma_f32 v73, v73, s92, v214
	v_fma_f32 v74, v74, s92, v214
	v_fma_f32 v75, v75, s92, v214
	v_fma_f32 v76, v76, s92, v214
	v_fma_f32 v77, v77, s92, v214
	v_fma_f32 v78, v78, s92, v214
	v_fma_f32 v79, v79, s92, v214
	s_cbranch_vccz .Lda_noresc_1
	s_and_saveexec_b64 s[12:13], s[40:41]
	ds_write_b32 v199, v213 offset:128
	s_or_b64 exec, exec, s[12:13]
	s_waitcnt lgkmcnt(0)
	v_add_u32_e32 v215, v99, v96
	ds_read_b128 v[228:231], v215 offset:128
	ds_read_b128 v[232:235], v215 offset:160
	ds_read_b128 v[236:239], v215 offset:192
	ds_read_b128 v[240:243], v215 offset:224
	s_waitcnt lgkmcnt(0)
	v_pk_mul_f32 v[0:1], v[0:1], v[228:229]
	v_pk_mul_f32 v[2:3], v[2:3], v[230:231]
	v_pk_mul_f32 v[4:5], v[4:5], v[232:233]
	v_pk_mul_f32 v[6:7], v[6:7], v[234:235]
	v_pk_mul_f32 v[8:9], v[8:9], v[236:237]
	v_pk_mul_f32 v[10:11], v[10:11], v[238:239]
	v_pk_mul_f32 v[12:13], v[12:13], v[240:241]
	v_pk_mul_f32 v[14:15], v[14:15], v[242:243]
	v_pk_mul_f32 v[48:49], v[48:49], v[228:229]
	v_pk_mul_f32 v[50:51], v[50:51], v[230:231]
	v_pk_mul_f32 v[52:53], v[52:53], v[232:233]
	v_pk_mul_f32 v[54:55], v[54:55], v[234:235]
	v_pk_mul_f32 v[56:57], v[56:57], v[236:237]
	v_pk_mul_f32 v[58:59], v[58:59], v[238:239]
	v_pk_mul_f32 v[60:61], v[60:61], v[240:241]
	v_pk_mul_f32 v[62:63], v[62:63], v[242:243]
	v_pk_mul_f32 v[32:33], v[32:33], v[228:229]
	v_pk_mul_f32 v[34:35], v[34:35], v[230:231]
	v_pk_mul_f32 v[36:37], v[36:37], v[232:233]
	v_pk_mul_f32 v[38:39], v[38:39], v[234:235]
	v_pk_mul_f32 v[40:41], v[40:41], v[236:237]
	v_pk_mul_f32 v[42:43], v[42:43], v[238:239]
	v_pk_mul_f32 v[44:45], v[44:45], v[240:241]
	v_pk_mul_f32 v[46:47], v[46:47], v[242:243]
	v_pk_mul_f32 v[16:17], v[16:17], v[228:229]
	v_pk_mul_f32 v[18:19], v[18:19], v[230:231]
	v_pk_mul_f32 v[20:21], v[20:21], v[232:233]
	v_pk_mul_f32 v[22:23], v[22:23], v[234:235]
	v_pk_mul_f32 v[24:25], v[24:25], v[236:237]
	v_pk_mul_f32 v[26:27], v[26:27], v[238:239]
	v_pk_mul_f32 v[28:29], v[28:29], v[240:241]
	v_pk_mul_f32 v[30:31], v[30:31], v[242:243]
.Lda_noresc_1:
	v_exp_f32_e32 v80, v80
	v_exp_f32_e32 v81, v81
	v_exp_f32_e32 v82, v82
	v_exp_f32_e32 v83, v83
	v_exp_f32_e32 v84, v84
	v_exp_f32_e32 v85, v85
	v_exp_f32_e32 v86, v86
	v_exp_f32_e32 v87, v87
	v_exp_f32_e32 v88, v88
	v_exp_f32_e32 v89, v89
	v_exp_f32_e32 v90, v90
	v_exp_f32_e32 v91, v91
	v_exp_f32_e32 v92, v92
	v_exp_f32_e32 v93, v93
	v_exp_f32_e32 v94, v94
	v_exp_f32_e32 v95, v95
	v_exp_f32_e32 v64, v64
	v_exp_f32_e32 v65, v65
	v_exp_f32_e32 v66, v66
	v_exp_f32_e32 v67, v67
	v_exp_f32_e32 v68, v68
	v_exp_f32_e32 v69, v69
	v_exp_f32_e32 v70, v70
	v_exp_f32_e32 v71, v71
	v_exp_f32_e32 v72, v72
	v_exp_f32_e32 v73, v73
	v_exp_f32_e32 v74, v74
	v_exp_f32_e32 v75, v75
	v_exp_f32_e32 v76, v76
	v_exp_f32_e32 v77, v77
	v_exp_f32_e32 v78, v78
	v_exp_f32_e32 v79, v79
	v_add_f32_e32 v201, v80, v81
	v_add_f32_e32 v202, v82, v83
	v_add_f32_e32 v201, v201, v84
	v_add_f32_e32 v202, v202, v85
	v_add_f32_e32 v201, v201, v86
	v_add_f32_e32 v202, v202, v87
	v_add_f32_e32 v201, v201, v88
	v_add_f32_e32 v202, v202, v89
	v_add_f32_e32 v201, v201, v90
	v_add_f32_e32 v202, v202, v91
	v_add_f32_e32 v201, v201, v92
	v_add_f32_e32 v202, v202, v93
	v_add_f32_e32 v201, v201, v94
	v_add_f32_e32 v202, v202, v95
	v_add_f32_e32 v201, v201, v64
	v_add_f32_e32 v202, v202, v65
	v_add_f32_e32 v201, v201, v66
	v_add_f32_e32 v202, v202, v67
	v_add_f32_e32 v201, v201, v68
	v_add_f32_e32 v202, v202, v69
	v_add_f32_e32 v201, v201, v70
	v_add_f32_e32 v202, v202, v71
	v_add_f32_e32 v201, v201, v72
	v_add_f32_e32 v202, v202, v73
	v_add_f32_e32 v201, v201, v74
	v_add_f32_e32 v202, v202, v75
	v_add_f32_e32 v201, v201, v76
	v_add_f32_e32 v202, v202, v77
	v_add_f32_e32 v201, v201, v78
	v_add_f32_e32 v202, v202, v79
	v_add_f32_e32 v201, v201, v202
	v_mov_b32_e32 v202, v201
	v_cvt_pk_bf16_f32 v166, v80, v81
	v_cvt_pk_bf16_f32 v167, v82, v83
	v_cvt_pk_bf16_f32 v168, v84, v85
	v_cvt_pk_bf16_f32 v169, v86, v87
	v_cvt_pk_bf16_f32 v170, v88, v89
	v_cvt_pk_bf16_f32 v171, v90, v91
	v_cvt_pk_bf16_f32 v172, v92, v93
	v_cvt_pk_bf16_f32 v173, v94, v95
	v_cvt_pk_bf16_f32 v176, v64, v65
	v_cvt_pk_bf16_f32 v177, v66, v67
	v_cvt_pk_bf16_f32 v178, v68, v69
	v_cvt_pk_bf16_f32 v179, v70, v71
	v_cvt_pk_bf16_f32 v180, v72, v73
	v_cvt_pk_bf16_f32 v181, v74, v75
	v_cvt_pk_bf16_f32 v182, v76, v77
	v_cvt_pk_bf16_f32 v183, v78, v79
	s_nop 1
	v_permlane32_swap_b32_e32 v201, v202
	v_permlane32_swap_b32_e32 v166, v168
	v_permlane32_swap_b32_e32 v167, v169
	v_permlane32_swap_b32_e32 v170, v172
	v_permlane32_swap_b32_e32 v171, v173
	v_permlane32_swap_b32_e32 v176, v178
	v_permlane32_swap_b32_e32 v177, v179
	v_permlane32_swap_b32_e32 v180, v182
	v_permlane32_swap_b32_e32 v181, v183
	v_add_f32_e32 v201, v201, v202
	v_fma_f32 v175, v175, v213, v201
	s_cmp_lt_u32 s31, 130
	s_cbranch_scc0 .Lda_skipw_1
	s_waitcnt vmcnt(0)
	ds_write_b128 v197, v[134:137] offset:49152
	ds_write_b128 v197, v[138:141] offset:57344
	ds_write_b128 v200, v[142:145] offset:49152
	ds_write_b128 v200, v[146:149] offset:57344
	s_nop 1

; #define SBAR() __builtin_amdgcn_sched_barrier(0)
; __device__ __forceinline__ void qkt(f32x16& p0, f32x16& p1, const bf16_t* Ks, const bf16x8* qr, int r32, int hi) {
;   p0 = f32x16{}; p1 = f32x16{};
; #pragma unroll
;   for (int d0 = 0; d0 < 8; ++d0) { int cb = (d0 * 16 + hi * 8) * 2;
;     bf16x8 b0 = *reinterpret_cast<const bf16x8*>((const char*)Ks + KSWZ(r32, cb));
;     bf16x8 b1 = *reinterpret_cast<const bf16x8*>((const char*)Ks + KSWZ(32 + r32, cb));
;     p0 = __builtin_amdgcn_mfma_f32_32x32x16_bf16(b0, qr[d0], p0, 0, 0, 0);
;     p1 = __builtin_amdgcn_mfma_f32_32x32x16_bf16(b1, qr[d0], p1, 0, 0, 0); }
; }
; __device__ __forceinline__ int v_st(int k, int c) { const int kk = (k & ~0xC) | ((k & 4) << 1) | ((k & 8) >> 1); return ((kk >> 3) * 4 + (c >> 5)) * 512 + ((kk & 7) * 32 + (c & 31)) * 2; }
; __device__ __forceinline__ int v_rd_base(int lane) { return ((lane & 3) << 3) | (((lane >> 2) & 3) << 6) | (((lane >> 4) & 1) << 5) | (((lane >> 5) & 1) << 8); }
; template <int OFF> __device__ __forceinline__ s16x4 tr_read(int vb) {
;   s16x4 r; asm volatile("ds_read_b64_tr_b16 %0, %1 offset:%2" : "=&v"(r) : "v"(vb), "i"(OFF) : "memory"); return r;
; }
; template <int D0> __device__ __forceinline__ void pv_one(f32x16& od, int vb, bf16x8 pa0, bf16x8 pa1, bf16x8 pa2, bf16x8 pa3) {
;   const s16x4 l0 = tr_read<v_rd_off(D0, 0, 0)>(vb), h0 = tr_read<v_rd_off(D0, 0, 1)>(vb), l1 = tr_read<v_rd_off(D0, 1, 0)>(vb), h1 = tr_read<v_rd_off(D0, 1, 1)>(vb);
;   const s16x4 l2 = tr_read<v_rd_off(D0, 2, 0)>(vb), h2 = tr_read<v_rd_off(D0, 2, 1)>(vb), l3 = tr_read<v_rd_off(D0, 3, 0)>(vb), h3 = tr_read<v_rd_off(D0, 3, 1)>(vb);
;   asm volatile("s_waitcnt lgkmcnt(0)" ::: "memory"); SBAR();
;     ...
;   od = __builtin_amdgcn_mfma_f32_32x32x16_bf16(pa0, PK(l0, h0), od, 0, 0, 0);
;   od = __builtin_amdgcn_mfma_f32_32x32x16_bf16(pa1, PK(l1, h1), od, 0, 0, 0);
;   od = __builtin_amdgcn_mfma_f32_32x32x16_bf16(pa2, PK(l2, h2), od, 0, 0, 0);
;   od = __builtin_amdgcn_mfma_f32_32x32x16_bf16(pa3, PK(l3, h3), od, 0, 0, 0);
;     ...
; }
; __device__ __forceinline__ void pv_d0(f32x16* o, int vb, bf16x8 pa0, bf16x8 pa1, bf16x8 pa2, bf16x8 pa3) {
;   pv_one<0>(o[0], vb, pa0, pa1, pa2, pa3); pv_one<1>(o[1], vb, pa0, pa1, pa2, pa3); pv_one<2>(o[2], vb, pa0, pa1, pa2, pa3); pv_one<3>(o[3], vb, pa0, pa1, pa2, pa3);
.Lda_skipl_1:
	s_add_u32 s31, s31, 1
	s_cmp_lt_u32 s31, 132
	s_cbranch_scc0 .Lda_skipk_1
	ds_read_b128 v[150:153], v204 offset:32768
	ds_read_b128 v[154:157], v204 offset:40960
	ds_read_b128 v[158:161], v205 offset:32768
	ds_read_b128 v[162:165], v205 offset:40960
	ds_read_b128 v[228:231], v206 offset:32768
	ds_read_b128 v[232:235], v206 offset:40960
	ds_read_b128 v[236:239], v207 offset:32768
	ds_read_b128 v[240:243], v207 offset:40960
.Lda_skipk_1:
	s_barrier
	s_waitcnt lgkmcnt(6)
	v_mfma_f32_32x32x16_bf16 v[80:95], v[150:153], v[130:133], 0
	v_mfma_f32_32x32x16_bf16 v[64:79], v[154:157], v[130:133], 0
	ds_read_b128 v[150:153], v208 offset:32768
	ds_read_b128 v[154:157], v208 offset:40960
	s_waitcnt lgkmcnt(6)
	v_mfma_f32_32x32x16_bf16 v[80:95], v[158:161], v[126:129], v[80:95]
	v_mfma_f32_32x32x16_bf16 v[64:79], v[162:165], v[126:129], v[64:79]
	ds_read_b128 v[158:161], v209 offset:32768
	ds_read_b128 v[162:165], v209 offset:40960
	s_waitcnt lgkmcnt(6)
	v_mfma_f32_32x32x16_bf16 v[80:95], v[228:231], v[122:125], v[80:95]
	v_mfma_f32_32x32x16_bf16 v[64:79], v[232:235], v[122:125], v[64:79]
	ds_read_b128 v[228:231], v210 offset:32768
	ds_read_b128 v[232:235], v210 offset:40960
	s_waitcnt lgkmcnt(6)
	v_mfma_f32_32x32x16_bf16 v[80:95], v[236:239], v[118:121], v[80:95]
	v_mfma_f32_32x32x16_bf16 v[64:79], v[240:243], v[118:121], v[64:79]
	ds_read_b128 v[236:239], v211 offset:32768
	ds_read_b128 v[240:243], v211 offset:40960
	s_waitcnt lgkmcnt(6)
	v_mfma_f32_32x32x16_bf16 v[80:95], v[150:153], v[114:117], v[80:95]
	v_mfma_f32_32x32x16_bf16 v[64:79], v[154:157], v[114:117], v[64:79]
	ds_read_b64_tr_b16 v[150:151], v196 offset:16384
	ds_read_b64_tr_b16 v[152:153], v196 offset:18432
	ds_read_b64_tr_b16 v[154:155], v196 offset:20480
	ds_read_b64_tr_b16 v[156:157], v196 offset:22528
	s_waitcnt lgkmcnt(8)
	v_mfma_f32_32x32x16_bf16 v[80:95], v[158:161], v[110:113], v[80:95]
	v_mfma_f32_32x32x16_bf16 v[64:79], v[162:165], v[110:113], v[64:79]
	ds_read_b64_tr_b16 v[158:159], v196 offset:24576
	ds_read_b64_tr_b16 v[160:161], v196 offset:26624
	ds_read_b64_tr_b16 v[162:163], v196 offset:28672
	ds_read_b64_tr_b16 v[164:165], v196 offset:30720
	s_waitcnt lgkmcnt(10)
	v_mfma_f32_32x32x16_bf16 v[80:95], v[228:231], v[106:109], v[80:95]
	v_mfma_f32_32x32x16_bf16 v[64:79], v[232:235], v[106:109], v[64:79]
	ds_read_b64_tr_b16 v[228:229], v196 offset:16896
	ds_read_b64_tr_b16 v[230:231], v196 offset:18944
	ds_read_b64_tr_b16 v[232:233], v196 offset:20992
	ds_read_b64_tr_b16 v[234:235], v196 offset:23040
	s_waitcnt lgkmcnt(12)
	v_mfma_f32_32x32x16_bf16 v[80:95], v[236:239], v[102:105], v[80:95]
	v_mfma_f32_32x32x16_bf16 v[64:79], v[240:243], v[102:105], v[64:79]
	ds_read_b64_tr_b16 v[236:237], v196 offset:25088
	ds_read_b64_tr_b16 v[238:239], v196 offset:27136
	s_waitcnt lgkmcnt(12)
	v_mfma_f32_32x32x16_bf16 v[0:15], v[166:169], v[150:153], v[0:15]
	ds_read_b64_tr_b16 v[240:241], v196 offset:29184
	ds_read_b64_tr_b16 v[242:243], v196 offset:31232
	s_waitcnt lgkmcnt(12)
	v_mfma_f32_32x32x16_bf16 v[0:15], v[170:173], v[154:157], v[0:15]
	ds_read_b64_tr_b16 v[150:151], v196 offset:17408
	ds_read_b64_tr_b16 v[152:153], v196 offset:19456
	s_waitcnt lgkmcnt(12)
	v_mfma_f32_32x32x16_bf16 v[0:15], v[176:179], v[158:161], v[0:15]
	ds_read_b64_tr_b16 v[154:155], v196 offset:21504
	ds_read_b64_tr_b16 v[156:157], v196 offset:23552
	s_waitcnt lgkmcnt(12)
	v_mfma_f32_32x32x16_bf16 v[0:15], v[180:183], v[162:165], v[0:15]
	ds_read_b64_tr_b16 v[158:159], v196 offset:25600
	ds_read_b64_tr_b16 v[160:161], v196 offset:27648
	s_waitcnt lgkmcnt(12)
	v_mfma_f32_32x32x16_bf16 v[48:63], v[166:169], v[228:231], v[48:63]
	ds_read_b64_tr_b16 v[162:163], v196 offset:29696
	ds_read_b64_tr_b16 v[164:165], v196 offset:31744
	s_waitcnt lgkmcnt(12)
	v_mfma_f32_32x32x16_bf16 v[48:63], v[170:173], v[232:235], v[48:63]
	ds_read_b64_tr_b16 v[228:229], v196 offset:17920
	ds_read_b64_tr_b16 v[230:231], v196 offset:19968
	s_waitcnt lgkmcnt(12)
	v_mfma_f32_32x32x16_bf16 v[48:63], v[176:179], v[236:239], v[48:63]
	ds_read_b64_tr_b16 v[232:233], v196 offset:22016
	ds_read_b64_tr_b16 v[234:235], v196 offset:24064
	s_waitcnt lgkmcnt(12)
	v_mfma_f32_32x32x16_bf16 v[48:63], v[180:183], v[240:243], v[48:63]
	ds_read_b64_tr_b16 v[236:237], v196 offset:26112
	ds_read_b64_tr_b16 v[238:239], v196 offset:28160
	s_waitcnt lgkmcnt(12)
	v_mfma_f32_32x32x16_bf16 v[32:47], v[166:169], v[150:153], v[32:47]
	ds_read_b64_tr_b16 v[240:241], v196 offset:30208
	ds_read_b64_tr_b16 v[242:243], v196 offset:32256
	s_waitcnt lgkmcnt(12)
	v_mfma_f32_32x32x16_bf16 v[32:47], v[170:173], v[154:157], v[32:47]
	s_waitcnt lgkmcnt(10)
	v_mfma_f32_32x32x16_bf16 v[32:47], v[176:179], v[158:161], v[32:47]
	s_waitcnt lgkmcnt(8)
	v_mfma_f32_32x32x16_bf16 v[32:47], v[180:183], v[162:165], v[32:47]
	s_waitcnt lgkmcnt(6)
	v_mfma_f32_32x32x16_bf16 v[16:31], v[166:169], v[228:231], v[16:31]
	s_waitcnt lgkmcnt(4)
	v_mfma_f32_32x32x16_bf16 v[16:31], v[170:173], v[232:235], v[16:31]
	s_waitcnt lgkmcnt(2)
	v_mfma_f32_32x32x16_bf16 v[16:31], v[176:179], v[236:239], v[16:31]
	s_waitcnt lgkmcnt(0)
	v_mfma_f32_32x32x16_bf16 v[16:31], v[180:183], v[240:243], v[16:31]
	s_barrier
; __device__ __forceinline__ void partialSM(f32x16& p0, f32x16& p1, float& m_reg, float& mn, float& alpha) {
;   constexpr float C = SCALE * 1.4426950408889634f;
;   float pmax = p0[0];
; #pragma unroll
;   for (int r = 1; r < 16; ++r) pmax = fmaxf(pmax, p0[r]);
; #pragma unroll
;   for (int r = 0; r < 16; ++r) pmax = fmaxf(pmax, p1[r]);
;   { auto rr = __builtin_amdgcn_permlane32_swap(__float_as_uint(pmax), __float_as_uint(pmax), false, false);
;     pmax = fmaxf(__uint_as_float(rr[0]), __uint_as_float(rr[1])); }
;   if (__builtin_expect(__all(pmax - m_reg <= THR / SCALE), 1)) { mn = m_reg; alpha = 1.f; }
;   else { mn = fmaxf(m_reg, pmax); alpha = __builtin_amdgcn_exp2f((m_reg - mn) * C); m_reg = mn; }
;   float mnC = -mn * C;
; #pragma unroll
;   for (int r = 0; r < 16; ++r) p0[r] = fmaf(p0[r], C, mnC);
; #pragma unroll
;   for (int r = 0; r < 16; ++r) p1[r] = fmaf(p1[r], C, mnC);
; #pragma unroll
;   for (int r = 0; r < 16; ++r) p0[r] = __builtin_amdgcn_exp2f(p0[r]);
; }
; __device__ __forceinline__ void finishSM(f32x16& p0, f32x16& p1, float alpha, float& l_reg, bf16x8& pa0, bf16x8& pa1, bf16x8& pa2, bf16x8& pa3) {
; #pragma unroll
;   for (int r = 0; r < 16; ++r) p1[r] = __builtin_amdgcn_exp2f(p1[r]);
;   float ps = 0;
; #pragma unroll
;   for (int r = 0; r < 16; ++r) ps += p0[r];
; #pragma unroll
;   for (int r = 0; r < 16; ++r) ps += p1[r];
;   { auto rr = __builtin_amdgcn_permlane32_swap(__float_as_uint(ps), __float_as_uint(ps), false, false);
;     ps = __uint_as_float(rr[0]) + __uint_as_float(rr[1]); }
;   l_reg = l_reg * alpha + ps;
;     ...
;   PK4(p0, 0, pa0); PK4(p0, 8, pa1); PK4(p1, 0, pa2); PK4(p1, 8, pa3);
;     ...
; }
	v_max3_f32 v201, v80, v81, v82
	v_max3_f32 v202, v64, v65, v66
	v_max3_f32 v201, v201, v83, v84
	v_max3_f32 v202, v202, v67, v68
	v_max3_f32 v201, v201, v85, v86
	v_max3_f32 v202, v202, v69, v70
	v_max3_f32 v201, v201, v87, v88
	v_max3_f32 v202, v202, v71, v72
	v_max3_f32 v201, v201, v89, v90
	v_max3_f32 v202, v202, v73, v74
	v_max3_f32 v201, v201, v91, v92
	v_max3_f32 v202, v202, v75, v76
	v_max3_f32 v201, v201, v93, v94
	v_max3_f32 v202, v202, v77, v78
	v_max3_f32 v201, v201, v95, v79
	v_max_f32_e32 v201, v201, v202
	v_mov_b32_e32 v202, v201
	s_nop 1
	v_permlane32_swap_b32_e32 v201, v202
	s_nop 0
	v_max_f32_e32 v212, v201, v202
	v_sub_f32_e32 v201, v212, v174
	v_cmp_ge_f32_e32 vcc, s86, v201
	v_max_f32_e32 v202, v174, v212
	v_sub_f32_e32 v215, v174, v202
	v_mul_f32_e32 v215, s92, v215
	s_nop 1
	s_cmp_eq_u64 vcc, exec
	s_cselect_b64 s[42:43], -1, 0
	v_exp_f32_e32 v213, v215
	s_nop 0
	v_cndmask_b32_e64 v174, v202, v174, s[42:43]
	v_cndmask_b32_e64 v213, v213, 1.0, s[42:43]
	v_mul_f32_e32 v214, 0xbe0293ee, v174
	s_nop 0
	v_cmp_gt_f32_e32 vcc, 1.0, v213
	v_fma_f32 v80, v80, s92, v214
	v_fma_f32 v81, v81, s92, v214
	v_fma_f32 v82, v82, s92, v214
	v_fma_f32 v83, v83, s92, v214
	v_fma_f32 v84, v84, s92, v214
	v_fma_f32 v85, v85, s92, v214
	v_fma_f32 v86, v86, s92, v214
	v_fma_f32 v87, v87, s92, v214
	v_fma_f32 v88, v88, s92, v214
	v_fma_f32 v89, v89, s92, v214
	v_fma_f32 v90, v90, s92, v214
	v_fma_f32 v91, v91, s92, v214
	v_fma_f32 v92, v92, s92, v214
	v_fma_f32 v93, v93, s92, v214
	v_fma_f32 v94, v94, s92, v214
	v_fma_f32 v95, v95, s92, v214
	v_fma_f32 v64, v64, s92, v214
	v_fma_f32 v65, v65, s92, v214
	v_fma_f32 v66, v66, s92, v214
	v_fma_f32 v67, v67, s92, v214
	v_fma_f32 v68, v68, s92, v214
	v_fma_f32 v69, v69, s92, v214
	v_fma_f32 v70, v70, s92, v214
	v_fma_f32 v71, v71, s92, v214
	v_fma_f32 v72, v72, s92, v214
	v_fma_f32 v73, v73, s92, v214
	v_fma_f32 v74, v74, s92, v214
	v_fma_f32 v75, v75, s92, v214
	v_fma_f32 v76, v76, s92, v214
	v_fma_f32 v77, v77, s92, v214
	v_fma_f32 v78, v78, s92, v214
	v_fma_f32 v79, v79, s92, v214
	s_cbranch_vccz .Lda_noresc_2
	s_and_saveexec_b64 s[12:13], s[40:41]
	ds_write_b32 v199, v213 offset:128
	s_or_b64 exec, exec, s[12:13]
	s_waitcnt lgkmcnt(0)
	v_add_u32_e32 v215, v99, v96
	ds_read_b128 v[228:231], v215 offset:128
	ds_read_b128 v[232:235], v215 offset:160
	ds_read_b128 v[236:239], v215 offset:192
	ds_read_b128 v[240:243], v215 offset:224
	s_waitcnt lgkmcnt(0)
	v_pk_mul_f32 v[0:1], v[0:1], v[228:229]
	v_pk_mul_f32 v[2:3], v[2:3], v[230:231]
	v_pk_mul_f32 v[4:5], v[4:5], v[232:233]
	v_pk_mul_f32 v[6:7], v[6:7], v[234:235]
	v_pk_mul_f32 v[8:9], v[8:9], v[236:237]
	v_pk_mul_f32 v[10:11], v[10:11], v[238:239]
	v_pk_mul_f32 v[12:13], v[12:13], v[240:241]
	v_pk_mul_f32 v[14:15], v[14:15], v[242:243]
	v_pk_mul_f32 v[48:49], v[48:49], v[228:229]
	v_pk_mul_f32 v[50:51], v[50:51], v[230:231]
	v_pk_mul_f32 v[52:53], v[52:53], v[232:233]
	v_pk_mul_f32 v[54:55], v[54:55], v[234:235]
	v_pk_mul_f32 v[56:57], v[56:57], v[236:237]
	v_pk_mul_f32 v[58:59], v[58:59], v[238:239]
	v_pk_mul_f32 v[60:61], v[60:61], v[240:241]
	v_pk_mul_f32 v[62:63], v[62:63], v[242:243]
	v_pk_mul_f32 v[32:33], v[32:33], v[228:229]
	v_pk_mul_f32 v[34:35], v[34:35], v[230:231]
	v_pk_mul_f32 v[36:37], v[36:37], v[232:233]
	v_pk_mul_f32 v[38:39], v[38:39], v[234:235]
	v_pk_mul_f32 v[40:41], v[40:41], v[236:237]
	v_pk_mul_f32 v[42:43], v[42:43], v[238:239]
	v_pk_mul_f32 v[44:45], v[44:45], v[240:241]
	v_pk_mul_f32 v[46:47], v[46:47], v[242:243]
	v_pk_mul_f32 v[16:17], v[16:17], v[228:229]
	v_pk_mul_f32 v[18:19], v[18:19], v[230:231]
	v_pk_mul_f32 v[20:21], v[20:21], v[232:233]
	v_pk_mul_f32 v[22:23], v[22:23], v[234:235]
	v_pk_mul_f32 v[24:25], v[24:25], v[236:237]
	v_pk_mul_f32 v[26:27], v[26:27], v[238:239]
	v_pk_mul_f32 v[28:29], v[28:29], v[240:241]
	v_pk_mul_f32 v[30:31], v[30:31], v[242:243]
.Lda_noresc_2:
	v_exp_f32_e32 v80, v80
	v_exp_f32_e32 v81, v81
	v_exp_f32_e32 v82, v82
	v_exp_f32_e32 v83, v83
	v_exp_f32_e32 v84, v84
	v_exp_f32_e32 v85, v85
	v_exp_f32_e32 v86, v86
	v_exp_f32_e32 v87, v87
	v_exp_f32_e32 v88, v88
	v_exp_f32_e32 v89, v89
	v_exp_f32_e32 v90, v90
	v_exp_f32_e32 v91, v91
	v_exp_f32_e32 v92, v92
	v_exp_f32_e32 v93, v93
	v_exp_f32_e32 v94, v94
	v_exp_f32_e32 v95, v95
	v_exp_f32_e32 v64, v64
	v_exp_f32_e32 v65, v65
	v_exp_f32_e32 v66, v66
	v_exp_f32_e32 v67, v67
	v_exp_f32_e32 v68, v68
	v_exp_f32_e32 v69, v69
	v_exp_f32_e32 v70, v70
	v_exp_f32_e32 v71, v71
	v_exp_f32_e32 v72, v72
	v_exp_f32_e32 v73, v73
	v_exp_f32_e32 v74, v74
	v_exp_f32_e32 v75, v75
	v_exp_f32_e32 v76, v76
	v_exp_f32_e32 v77, v77
	v_exp_f32_e32 v78, v78
	v_exp_f32_e32 v79, v79
	v_add_f32_e32 v201, v80, v81
	v_add_f32_e32 v202, v82, v83
	v_add_f32_e32 v201, v201, v84
	v_add_f32_e32 v202, v202, v85
	v_add_f32_e32 v201, v201, v86
	v_add_f32_e32 v202, v202, v87
	v_add_f32_e32 v201, v201, v88
	v_add_f32_e32 v202, v202, v89
	v_add_f32_e32 v201, v201, v90
	v_add_f32_e32 v202, v202, v91
	v_add_f32_e32 v201, v201, v92
	v_add_f32_e32 v202, v202, v93
	v_add_f32_e32 v201, v201, v94
	v_add_f32_e32 v202, v202, v95
	v_add_f32_e32 v201, v201, v64
	v_add_f32_e32 v202, v202, v65
	v_add_f32_e32 v201, v201, v66
	v_add_f32_e32 v202, v202, v67
	v_add_f32_e32 v201, v201, v68
	v_add_f32_e32 v202, v202, v69
	v_add_f32_e32 v201, v201, v70
	v_add_f32_e32 v202, v202, v71
	v_add_f32_e32 v201, v201, v72
	v_add_f32_e32 v202, v202, v73
	v_add_f32_e32 v201, v201, v74
	v_add_f32_e32 v202, v202, v75
	v_add_f32_e32 v201, v201, v76
	v_add_f32_e32 v202, v202, v77
	v_add_f32_e32 v201, v201, v78
	v_add_f32_e32 v202, v202, v79
	v_add_f32_e32 v201, v201, v202
	v_mov_b32_e32 v202, v201
	v_cvt_pk_bf16_f32 v166, v80, v81
	v_cvt_pk_bf16_f32 v167, v82, v83
	v_cvt_pk_bf16_f32 v168, v84, v85
	v_cvt_pk_bf16_f32 v169, v86, v87
	v_cvt_pk_bf16_f32 v170, v88, v89
	v_cvt_pk_bf16_f32 v171, v90, v91
	v_cvt_pk_bf16_f32 v172, v92, v93
	v_cvt_pk_bf16_f32 v173, v94, v95
	v_cvt_pk_bf16_f32 v176, v64, v65
	v_cvt_pk_bf16_f32 v177, v66, v67
	v_cvt_pk_bf16_f32 v178, v68, v69
	v_cvt_pk_bf16_f32 v179, v70, v71
	v_cvt_pk_bf16_f32 v180, v72, v73
	v_cvt_pk_bf16_f32 v181, v74, v75
	v_cvt_pk_bf16_f32 v182, v76, v77
	v_cvt_pk_bf16_f32 v183, v78, v79
	s_nop 1
	v_permlane32_swap_b32_e32 v201, v202
	v_permlane32_swap_b32_e32 v166, v168
	v_permlane32_swap_b32_e32 v167, v169
	v_permlane32_swap_b32_e32 v170, v172
	v_permlane32_swap_b32_e32 v171, v173
	v_permlane32_swap_b32_e32 v176, v178
	v_permlane32_swap_b32_e32 v177, v179
	v_permlane32_swap_b32_e32 v180, v182
	v_permlane32_swap_b32_e32 v181, v183
	v_add_f32_e32 v201, v201, v202
	v_fma_f32 v175, v175, v213, v201
	s_cmp_lt_u32 s31, 130
	s_cbranch_scc0 .Lda_skipw_2
	s_waitcnt vmcnt(0)
	ds_write_b128 v197, v[134:137] offset:0
	ds_write_b128 v197, v[138:141] offset:8192
	ds_write_b128 v200, v[142:145] offset:0
	ds_write_b128 v200, v[146:149] offset:8192
	s_nop 1

; #define SBAR() __builtin_amdgcn_sched_barrier(0)
; __device__ __forceinline__ void qkt(f32x16& p0, f32x16& p1, const bf16_t* Ks, const bf16x8* qr, int r32, int hi) {
;   p0 = f32x16{}; p1 = f32x16{};
; #pragma unroll
;   for (int d0 = 0; d0 < 8; ++d0) { int cb = (d0 * 16 + hi * 8) * 2;
;     bf16x8 b0 = *reinterpret_cast<const bf16x8*>((const char*)Ks + KSWZ(r32, cb));
;     bf16x8 b1 = *reinterpret_cast<const bf16x8*>((const char*)Ks + KSWZ(32 + r32, cb));
;     p0 = __builtin_amdgcn_mfma_f32_32x32x16_bf16(b0, qr[d0], p0, 0, 0, 0);
;     p1 = __builtin_amdgcn_mfma_f32_32x32x16_bf16(b1, qr[d0], p1, 0, 0, 0); }
; }
; __device__ __forceinline__ int v_st(int k, int c) { const int kk = (k & ~0xC) | ((k & 4) << 1) | ((k & 8) >> 1); return ((kk >> 3) * 4 + (c >> 5)) * 512 + ((kk & 7) * 32 + (c & 31)) * 2; }
; __device__ __forceinline__ int v_rd_base(int lane) { return ((lane & 3) << 3) | (((lane >> 2) & 3) << 6) | (((lane >> 4) & 1) << 5) | (((lane >> 5) & 1) << 8); }
; template <int OFF> __device__ __forceinline__ s16x4 tr_read(int vb) {
;   s16x4 r; asm volatile("ds_read_b64_tr_b16 %0, %1 offset:%2" : "=&v"(r) : "v"(vb), "i"(OFF) : "memory"); return r;
; }
; template <int D0> __device__ __forceinline__ void pv_one(f32x16& od, int vb, bf16x8 pa0, bf16x8 pa1, bf16x8 pa2, bf16x8 pa3) {
;   const s16x4 l0 = tr_read<v_rd_off(D0, 0, 0)>(vb), h0 = tr_read<v_rd_off(D0, 0, 1)>(vb), l1 = tr_read<v_rd_off(D0, 1, 0)>(vb), h1 = tr_read<v_rd_off(D0, 1, 1)>(vb);
;   const s16x4 l2 = tr_read<v_rd_off(D0, 2, 0)>(vb), h2 = tr_read<v_rd_off(D0, 2, 1)>(vb), l3 = tr_read<v_rd_off(D0, 3, 0)>(vb), h3 = tr_read<v_rd_off(D0, 3, 1)>(vb);
;   asm volatile("s_waitcnt lgkmcnt(0)" ::: "memory"); SBAR();
;     ...
;   od = __builtin_amdgcn_mfma_f32_32x32x16_bf16(pa0, PK(l0, h0), od, 0, 0, 0);
;   od = __builtin_amdgcn_mfma_f32_32x32x16_bf16(pa1, PK(l1, h1), od, 0, 0, 0);
;   od = __builtin_amdgcn_mfma_f32_32x32x16_bf16(pa2, PK(l2, h2), od, 0, 0, 0);
;   od = __builtin_amdgcn_mfma_f32_32x32x16_bf16(pa3, PK(l3, h3), od, 0, 0, 0);
;     ...
; }
; __device__ __forceinline__ void pv_d0(f32x16* o, int vb, bf16x8 pa0, bf16x8 pa1, bf16x8 pa2, bf16x8 pa3) {
;   pv_one<0>(o[0], vb, pa0, pa1, pa2, pa3); pv_one<1>(o[1], vb, pa0, pa1, pa2, pa3); pv_one<2>(o[2], vb, pa0, pa1, pa2, pa3); pv_one<3>(o[3], vb, pa0, pa1, pa2, pa3);
.Lda_skipl_2:
	s_add_u32 s31, s31, 1
	s_cmp_lt_u32 s31, 132
	s_cbranch_scc0 .Lda_skipk_2
	ds_read_b128 v[150:153], v204 offset:49152
	ds_read_b128 v[154:157], v204 offset:57344
	ds_read_b128 v[158:161], v205 offset:49152
	ds_read_b128 v[162:165], v205 offset:57344
	ds_read_b128 v[228:231], v206 offset:49152
	ds_read_b128 v[232:235], v206 offset:57344
	ds_read_b128 v[236:239], v207 offset:49152
	ds_read_b128 v[240:243], v207 offset:57344
.Lda_skipk_2:
	s_barrier
	s_waitcnt lgkmcnt(6)
	v_mfma_f32_32x32x16_bf16 v[80:95], v[150:153], v[130:133], 0
	v_mfma_f32_32x32x16_bf16 v[64:79], v[154:157], v[130:133], 0
	ds_read_b128 v[150:153], v208 offset:49152
	ds_read_b128 v[154:157], v208 offset:57344
	s_waitcnt lgkmcnt(6)
	v_mfma_f32_32x32x16_bf16 v[80:95], v[158:161], v[126:129], v[80:95]
	v_mfma_f32_32x32x16_bf16 v[64:79], v[162:165], v[126:129], v[64:79]
	ds_read_b128 v[158:161], v209 offset:49152
	ds_read_b128 v[162:165], v209 offset:57344
	s_waitcnt lgkmcnt(6)
	v_mfma_f32_32x32x16_bf16 v[80:95], v[228:231], v[122:125], v[80:95]
	v_mfma_f32_32x32x16_bf16 v[64:79], v[232:235], v[122:125], v[64:79]
	ds_read_b128 v[228:231], v210 offset:49152
	ds_read_b128 v[232:235], v210 offset:57344
	s_waitcnt lgkmcnt(6)
	v_mfma_f32_32x32x16_bf16 v[80:95], v[236:239], v[118:121], v[80:95]
	v_mfma_f32_32x32x16_bf16 v[64:79], v[240:243], v[118:121], v[64:79]
	ds_read_b128 v[236:239], v211 offset:49152
	ds_read_b128 v[240:243], v211 offset:57344
	s_waitcnt lgkmcnt(6)
	v_mfma_f32_32x32x16_bf16 v[80:95], v[150:153], v[114:117], v[80:95]
	v_mfma_f32_32x32x16_bf16 v[64:79], v[154:157], v[114:117], v[64:79]
	ds_read_b64_tr_b16 v[150:151], v196 offset:32768
	ds_read_b64_tr_b16 v[152:153], v196 offset:34816
	ds_read_b64_tr_b16 v[154:155], v196 offset:36864
	ds_read_b64_tr_b16 v[156:157], v196 offset:38912
	s_waitcnt lgkmcnt(8)
	v_mfma_f32_32x32x16_bf16 v[80:95], v[158:161], v[110:113], v[80:95]
	v_mfma_f32_32x32x16_bf16 v[64:79], v[162:165], v[110:113], v[64:79]
	ds_read_b64_tr_b16 v[158:159], v196 offset:40960
	ds_read_b64_tr_b16 v[160:161], v196 offset:43008
	ds_read_b64_tr_b16 v[162:163], v196 offset:45056
	ds_read_b64_tr_b16 v[164:165], v196 offset:47104
	s_waitcnt lgkmcnt(10)
	v_mfma_f32_32x32x16_bf16 v[80:95], v[228:231], v[106:109], v[80:95]
	v_mfma_f32_32x32x16_bf16 v[64:79], v[232:235], v[106:109], v[64:79]
	ds_read_b64_tr_b16 v[228:229], v196 offset:33280
	ds_read_b64_tr_b16 v[230:231], v196 offset:35328
	ds_read_b64_tr_b16 v[232:233], v196 offset:37376
	ds_read_b64_tr_b16 v[234:235], v196 offset:39424
	s_waitcnt lgkmcnt(12)
	v_mfma_f32_32x32x16_bf16 v[80:95], v[236:239], v[102:105], v[80:95]
	v_mfma_f32_32x32x16_bf16 v[64:79], v[240:243], v[102:105], v[64:79]
	ds_read_b64_tr_b16 v[236:237], v196 offset:41472
	ds_read_b64_tr_b16 v[238:239], v196 offset:43520
	s_waitcnt lgkmcnt(12)
	v_mfma_f32_32x32x16_bf16 v[0:15], v[166:169], v[150:153], v[0:15]
	ds_read_b64_tr_b16 v[240:241], v196 offset:45568
	ds_read_b64_tr_b16 v[242:243], v196 offset:47616
	s_waitcnt lgkmcnt(12)
	v_mfma_f32_32x32x16_bf16 v[0:15], v[170:173], v[154:157], v[0:15]
	ds_read_b64_tr_b16 v[150:151], v196 offset:33792
	ds_read_b64_tr_b16 v[152:153], v196 offset:35840
	s_waitcnt lgkmcnt(12)
	v_mfma_f32_32x32x16_bf16 v[0:15], v[176:179], v[158:161], v[0:15]
	ds_read_b64_tr_b16 v[154:155], v196 offset:37888
	ds_read_b64_tr_b16 v[156:157], v196 offset:39936
	s_waitcnt lgkmcnt(12)
	v_mfma_f32_32x32x16_bf16 v[0:15], v[180:183], v[162:165], v[0:15]
	ds_read_b64_tr_b16 v[158:159], v196 offset:41984
	ds_read_b64_tr_b16 v[160:161], v196 offset:44032
	s_waitcnt lgkmcnt(12)
	v_mfma_f32_32x32x16_bf16 v[48:63], v[166:169], v[228:231], v[48:63]
	ds_read_b64_tr_b16 v[162:163], v196 offset:46080
	ds_read_b64_tr_b16 v[164:165], v196 offset:48128
	s_waitcnt lgkmcnt(12)
	v_mfma_f32_32x32x16_bf16 v[48:63], v[170:173], v[232:235], v[48:63]
	ds_read_b64_tr_b16 v[228:229], v196 offset:34304
	ds_read_b64_tr_b16 v[230:231], v196 offset:36352
	s_waitcnt lgkmcnt(12)
	v_mfma_f32_32x32x16_bf16 v[48:63], v[176:179], v[236:239], v[48:63]
	ds_read_b64_tr_b16 v[232:233], v196 offset:38400
	ds_read_b64_tr_b16 v[234:235], v196 offset:40448
	s_waitcnt lgkmcnt(12)
	v_mfma_f32_32x32x16_bf16 v[48:63], v[180:183], v[240:243], v[48:63]
	ds_read_b64_tr_b16 v[236:237], v196 offset:42496
	ds_read_b64_tr_b16 v[238:239], v196 offset:44544
	s_waitcnt lgkmcnt(12)
	v_mfma_f32_32x32x16_bf16 v[32:47], v[166:169], v[150:153], v[32:47]
	ds_read_b64_tr_b16 v[240:241], v196 offset:46592
	ds_read_b64_tr_b16 v[242:243], v196 offset:48640
	s_waitcnt lgkmcnt(12)
	v_mfma_f32_32x32x16_bf16 v[32:47], v[170:173], v[154:157], v[32:47]
	s_waitcnt lgkmcnt(10)
	v_mfma_f32_32x32x16_bf16 v[32:47], v[176:179], v[158:161], v[32:47]
	s_waitcnt lgkmcnt(8)
	v_mfma_f32_32x32x16_bf16 v[32:47], v[180:183], v[162:165], v[32:47]
	s_waitcnt lgkmcnt(6)
	v_mfma_f32_32x32x16_bf16 v[16:31], v[166:169], v[228:231], v[16:31]
	s_waitcnt lgkmcnt(4)
	v_mfma_f32_32x32x16_bf16 v[16:31], v[170:173], v[232:235], v[16:31]
	s_waitcnt lgkmcnt(2)
	v_mfma_f32_32x32x16_bf16 v[16:31], v[176:179], v[236:239], v[16:31]
	s_waitcnt lgkmcnt(0)
	v_mfma_f32_32x32x16_bf16 v[16:31], v[180:183], v[240:243], v[16:31]
	s_barrier
; __device__ __forceinline__ void partialSM(f32x16& p0, f32x16& p1, float& m_reg, float& mn, float& alpha) {
;   constexpr float C = SCALE * 1.4426950408889634f;
;   float pmax = p0[0];
; #pragma unroll
;   for (int r = 1; r < 16; ++r) pmax = fmaxf(pmax, p0[r]);
; #pragma unroll
;   for (int r = 0; r < 16; ++r) pmax = fmaxf(pmax, p1[r]);
;   { auto rr = __builtin_amdgcn_permlane32_swap(__float_as_uint(pmax), __float_as_uint(pmax), false, false);
;     pmax = fmaxf(__uint_as_float(rr[0]), __uint_as_float(rr[1])); }
;   if (__builtin_expect(__all(pmax - m_reg <= THR / SCALE), 1)) { mn = m_reg; alpha = 1.f; }
;   else { mn = fmaxf(m_reg, pmax); alpha = __builtin_amdgcn_exp2f((m_reg - mn) * C); m_reg = mn; }
;   float mnC = -mn * C;
; #pragma unroll
;   for (int r = 0; r < 16; ++r) p0[r] = fmaf(p0[r], C, mnC);
; #pragma unroll
;   for (int r = 0; r < 16; ++r) p1[r] = fmaf(p1[r], C, mnC);
; #pragma unroll
;   for (int r = 0; r < 16; ++r) p0[r] = __builtin_amdgcn_exp2f(p0[r]);
; }
; __device__ __forceinline__ void finishSM(f32x16& p0, f32x16& p1, float alpha, float& l_reg, bf16x8& pa0, bf16x8& pa1, bf16x8& pa2, bf16x8& pa3) {
; #pragma unroll
;   for (int r = 0; r < 16; ++r) p1[r] = __builtin_amdgcn_exp2f(p1[r]);
;   float ps = 0;
; #pragma unroll
;   for (int r = 0; r < 16; ++r) ps += p0[r];
; #pragma unroll
;   for (int r = 0; r < 16; ++r) ps += p1[r];
;   { auto rr = __builtin_amdgcn_permlane32_swap(__float_as_uint(ps), __float_as_uint(ps), false, false);
;     ps = __uint_as_float(rr[0]) + __uint_as_float(rr[1]); }
;   l_reg = l_reg * alpha + ps;
;     ...
;   PK4(p0, 0, pa0); PK4(p0, 8, pa1); PK4(p1, 0, pa2); PK4(p1, 8, pa3);
;     ...
; }
	v_max3_f32 v201, v80, v81, v82
	v_max3_f32 v202, v64, v65, v66
	v_max3_f32 v201, v201, v83, v84
	v_max3_f32 v202, v202, v67, v68
	v_max3_f32 v201, v201, v85, v86
	v_max3_f32 v202, v202, v69, v70
	v_max3_f32 v201, v201, v87, v88
	v_max3_f32 v202, v202, v71, v72
	v_max3_f32 v201, v201, v89, v90
	v_max3_f32 v202, v202, v73, v74
	v_max3_f32 v201, v201, v91, v92
	v_max3_f32 v202, v202, v75, v76
	v_max3_f32 v201, v201, v93, v94
	v_max3_f32 v202, v202, v77, v78
	v_max3_f32 v201, v201, v95, v79
	v_max_f32_e32 v201, v201, v202
	v_mov_b32_e32 v202, v201
	s_nop 1
	v_permlane32_swap_b32_e32 v201, v202
	s_nop 0
	v_max_f32_e32 v212, v201, v202
	v_sub_f32_e32 v201, v212, v174
	v_cmp_ge_f32_e32 vcc, s86, v201
	v_max_f32_e32 v202, v174, v212
	v_sub_f32_e32 v215, v174, v202
	v_mul_f32_e32 v215, s92, v215
	s_nop 1
	s_cmp_eq_u64 vcc, exec
	s_cselect_b64 s[42:43], -1, 0
	v_exp_f32_e32 v213, v215
	s_nop 0
	v_cndmask_b32_e64 v174, v202, v174, s[42:43]
	v_cndmask_b32_e64 v213, v213, 1.0, s[42:43]
	v_mul_f32_e32 v214, 0xbe0293ee, v174
	s_nop 0
	v_cmp_gt_f32_e32 vcc, 1.0, v213
	v_fma_f32 v80, v80, s92, v214
	v_fma_f32 v81, v81, s92, v214
	v_fma_f32 v82, v82, s92, v214
	v_fma_f32 v83, v83, s92, v214
	v_fma_f32 v84, v84, s92, v214
	v_fma_f32 v85, v85, s92, v214
	v_fma_f32 v86, v86, s92, v214
	v_fma_f32 v87, v87, s92, v214
	v_fma_f32 v88, v88, s92, v214
	v_fma_f32 v89, v89, s92, v214
	v_fma_f32 v90, v90, s92, v214
	v_fma_f32 v91, v91, s92, v214
	v_fma_f32 v92, v92, s92, v214
	v_fma_f32 v93, v93, s92, v214
	v_fma_f32 v94, v94, s92, v214
	v_fma_f32 v95, v95, s92, v214
	v_fma_f32 v64, v64, s92, v214
	v_fma_f32 v65, v65, s92, v214
	v_fma_f32 v66, v66, s92, v214
	v_fma_f32 v67, v67, s92, v214
	v_fma_f32 v68, v68, s92, v214
	v_fma_f32 v69, v69, s92, v214
	v_fma_f32 v70, v70, s92, v214
	v_fma_f32 v71, v71, s92, v214
	v_fma_f32 v72, v72, s92, v214
	v_fma_f32 v73, v73, s92, v214
	v_fma_f32 v74, v74, s92, v214
	v_fma_f32 v75, v75, s92, v214
	v_fma_f32 v76, v76, s92, v214
	v_fma_f32 v77, v77, s92, v214
	v_fma_f32 v78, v78, s92, v214
	v_fma_f32 v79, v79, s92, v214
	s_cbranch_vccz .Lda_noresc_3
	s_and_saveexec_b64 s[12:13], s[40:41]
	ds_write_b32 v199, v213 offset:128
	s_or_b64 exec, exec, s[12:13]
	s_waitcnt lgkmcnt(0)
	v_add_u32_e32 v215, v99, v96
	ds_read_b128 v[228:231], v215 offset:128
	ds_read_b128 v[232:235], v215 offset:160
	ds_read_b128 v[236:239], v215 offset:192
	ds_read_b128 v[240:243], v215 offset:224
	s_waitcnt lgkmcnt(0)
	v_pk_mul_f32 v[0:1], v[0:1], v[228:229]
	v_pk_mul_f32 v[2:3], v[2:3], v[230:231]
	v_pk_mul_f32 v[4:5], v[4:5], v[232:233]
	v_pk_mul_f32 v[6:7], v[6:7], v[234:235]
	v_pk_mul_f32 v[8:9], v[8:9], v[236:237]
	v_pk_mul_f32 v[10:11], v[10:11], v[238:239]
	v_pk_mul_f32 v[12:13], v[12:13], v[240:241]
	v_pk_mul_f32 v[14:15], v[14:15], v[242:243]
	v_pk_mul_f32 v[48:49], v[48:49], v[228:229]
	v_pk_mul_f32 v[50:51], v[50:51], v[230:231]
	v_pk_mul_f32 v[52:53], v[52:53], v[232:233]
	v_pk_mul_f32 v[54:55], v[54:55], v[234:235]
	v_pk_mul_f32 v[56:57], v[56:57], v[236:237]
	v_pk_mul_f32 v[58:59], v[58:59], v[238:239]
	v_pk_mul_f32 v[60:61], v[60:61], v[240:241]
	v_pk_mul_f32 v[62:63], v[62:63], v[242:243]
	v_pk_mul_f32 v[32:33], v[32:33], v[228:229]
	v_pk_mul_f32 v[34:35], v[34:35], v[230:231]
	v_pk_mul_f32 v[36:37], v[36:37], v[232:233]
	v_pk_mul_f32 v[38:39], v[38:39], v[234:235]
	v_pk_mul_f32 v[40:41], v[40:41], v[236:237]
	v_pk_mul_f32 v[42:43], v[42:43], v[238:239]
	v_pk_mul_f32 v[44:45], v[44:45], v[240:241]
	v_pk_mul_f32 v[46:47], v[46:47], v[242:243]
	v_pk_mul_f32 v[16:17], v[16:17], v[228:229]
	v_pk_mul_f32 v[18:19], v[18:19], v[230:231]
	v_pk_mul_f32 v[20:21], v[20:21], v[232:233]
	v_pk_mul_f32 v[22:23], v[22:23], v[234:235]
	v_pk_mul_f32 v[24:25], v[24:25], v[236:237]
	v_pk_mul_f32 v[26:27], v[26:27], v[238:239]
	v_pk_mul_f32 v[28:29], v[28:29], v[240:241]
	v_pk_mul_f32 v[30:31], v[30:31], v[242:243]
.Lda_noresc_3:
	v_exp_f32_e32 v80, v80
	v_exp_f32_e32 v81, v81
	v_exp_f32_e32 v82, v82
	v_exp_f32_e32 v83, v83
	v_exp_f32_e32 v84, v84
	v_exp_f32_e32 v85, v85
	v_exp_f32_e32 v86, v86
	v_exp_f32_e32 v87, v87
	v_exp_f32_e32 v88, v88
	v_exp_f32_e32 v89, v89
	v_exp_f32_e32 v90, v90
	v_exp_f32_e32 v91, v91
	v_exp_f32_e32 v92, v92
	v_exp_f32_e32 v93, v93
	v_exp_f32_e32 v94, v94
	v_exp_f32_e32 v95, v95
	v_exp_f32_e32 v64, v64
	v_exp_f32_e32 v65, v65
	v_exp_f32_e32 v66, v66
	v_exp_f32_e32 v67, v67
	v_exp_f32_e32 v68, v68
	v_exp_f32_e32 v69, v69
	v_exp_f32_e32 v70, v70
	v_exp_f32_e32 v71, v71
	v_exp_f32_e32 v72, v72
	v_exp_f32_e32 v73, v73
	v_exp_f32_e32 v74, v74
	v_exp_f32_e32 v75, v75
	v_exp_f32_e32 v76, v76
	v_exp_f32_e32 v77, v77
	v_exp_f32_e32 v78, v78
	v_exp_f32_e32 v79, v79
	v_add_f32_e32 v201, v80, v81
	v_add_f32_e32 v202, v82, v83
	v_add_f32_e32 v201, v201, v84
	v_add_f32_e32 v202, v202, v85
	v_add_f32_e32 v201, v201, v86
	v_add_f32_e32 v202, v202, v87
	v_add_f32_e32 v201, v201, v88
	v_add_f32_e32 v202, v202, v89
	v_add_f32_e32 v201, v201, v90
	v_add_f32_e32 v202, v202, v91
	v_add_f32_e32 v201, v201, v92
	v_add_f32_e32 v202, v202, v93
	v_add_f32_e32 v201, v201, v94
	v_add_f32_e32 v202, v202, v95
	v_add_f32_e32 v201, v201, v64
	v_add_f32_e32 v202, v202, v65
	v_add_f32_e32 v201, v201, v66
	v_add_f32_e32 v202, v202, v67
	v_add_f32_e32 v201, v201, v68
	v_add_f32_e32 v202, v202, v69
	v_add_f32_e32 v201, v201, v70
	v_add_f32_e32 v202, v202, v71
	v_add_f32_e32 v201, v201, v72
	v_add_f32_e32 v202, v202, v73
	v_add_f32_e32 v201, v201, v74
	v_add_f32_e32 v202, v202, v75
	v_add_f32_e32 v201, v201, v76
	v_add_f32_e32 v202, v202, v77
	v_add_f32_e32 v201, v201, v78
	v_add_f32_e32 v202, v202, v79
	v_add_f32_e32 v201, v201, v202
	v_mov_b32_e32 v202, v201
	v_cvt_pk_bf16_f32 v166, v80, v81
	v_cvt_pk_bf16_f32 v167, v82, v83
	v_cvt_pk_bf16_f32 v168, v84, v85
	v_cvt_pk_bf16_f32 v169, v86, v87
	v_cvt_pk_bf16_f32 v170, v88, v89
	v_cvt_pk_bf16_f32 v171, v90, v91
	v_cvt_pk_bf16_f32 v172, v92, v93
	v_cvt_pk_bf16_f32 v173, v94, v95
	v_cvt_pk_bf16_f32 v176, v64, v65
	v_cvt_pk_bf16_f32 v177, v66, v67
	v_cvt_pk_bf16_f32 v178, v68, v69
	v_cvt_pk_bf16_f32 v179, v70, v71
	v_cvt_pk_bf16_f32 v180, v72, v73
	v_cvt_pk_bf16_f32 v181, v74, v75
	v_cvt_pk_bf16_f32 v182, v76, v77
	v_cvt_pk_bf16_f32 v183, v78, v79
	s_nop 1
	v_permlane32_swap_b32_e32 v201, v202
	v_permlane32_swap_b32_e32 v166, v168
	v_permlane32_swap_b32_e32 v167, v169
	v_permlane32_swap_b32_e32 v170, v172
	v_permlane32_swap_b32_e32 v171, v173
	v_permlane32_swap_b32_e32 v176, v178
	v_permlane32_swap_b32_e32 v177, v179
	v_permlane32_swap_b32_e32 v180, v182
	v_permlane32_swap_b32_e32 v181, v183
	v_add_f32_e32 v201, v201, v202
	v_fma_f32 v175, v175, v213, v201
	s_cmp_lt_u32 s31, 130
	s_cbranch_scc0 .Lda_skipw_3
	s_waitcnt vmcnt(0)
	ds_write_b128 v197, v[134:137] offset:16384
	ds_write_b128 v197, v[138:141] offset:24576
	ds_write_b128 v200, v[142:145] offset:16384
	ds_write_b128 v200, v[146:149] offset:24576
	s_nop 1

; #define SBAR() __builtin_amdgcn_sched_barrier(0)
; #define RESC(a) do { if (__any((a) < 1.f)) { if (hi == 0) al_l[r32] = (a); asm volatile("s_waitcnt lgkmcnt(0)" ::: "memory"); \
;     _Pragma("unroll") for (int d = 0; d < 4; ++d) _Pragma("unroll") for (int r = 0; r < 16; ++r) o[d][r] *= al_l[crow(r, hi)]; } } while (0)
; template <int D0> __device__ __forceinline__ void pv_one(f32x16& od, int vb, bf16x8 pa0, bf16x8 pa1, bf16x8 pa2, bf16x8 pa3) {
;   const s16x4 l0 = tr_read<v_rd_off(D0, 0, 0)>(vb), h0 = tr_read<v_rd_off(D0, 0, 1)>(vb), l1 = tr_read<v_rd_off(D0, 1, 0)>(vb), h1 = tr_read<v_rd_off(D0, 1, 1)>(vb);
;   const s16x4 l2 = tr_read<v_rd_off(D0, 2, 0)>(vb), h2 = tr_read<v_rd_off(D0, 2, 1)>(vb), l3 = tr_read<v_rd_off(D0, 3, 0)>(vb), h3 = tr_read<v_rd_off(D0, 3, 1)>(vb);
;   asm volatile("s_waitcnt lgkmcnt(0)" ::: "memory"); SBAR();
;     ...
;   od = __builtin_amdgcn_mfma_f32_32x32x16_bf16(pa0, PK(l0, h0), od, 0, 0, 0);
;   od = __builtin_amdgcn_mfma_f32_32x32x16_bf16(pa1, PK(l1, h1), od, 0, 0, 0);
;   od = __builtin_amdgcn_mfma_f32_32x32x16_bf16(pa2, PK(l2, h2), od, 0, 0, 0);
;   od = __builtin_amdgcn_mfma_f32_32x32x16_bf16(pa3, PK(l3, h3), od, 0, 0, 0);
;     ...
; }
; __device__ __forceinline__ void pv_d0(f32x16* o, int vb, bf16x8 pa0, bf16x8 pa1, bf16x8 pa2, bf16x8 pa3) {
;   pv_one<0>(o[0], vb, pa0, pa1, pa2, pa3); pv_one<1>(o[1], vb, pa0, pa1, pa2, pa3); pv_one<2>(o[2], vb, pa0, pa1, pa2, pa3); pv_one<3>(o[3], vb, pa0, pa1, pa2, pa3);
; template <int MODE, int SDEPTH>
; __device__ __forceinline__ void attn_unit(const UnitP& u, char* lds) {
;     ...
;   SBAR(); qkt(pB0, pB1, (bf16_t*)((char*)K_lds + SHM_K), qr, r32, hi);
;   finishSM(pA0, pA1, alA, l_reg, pa0, pa1, pa2, pa3); SBAR();
;   pv_d0(o, vb0, pa0, pa1, pa2, pa3); mask_tile<MODE>(pB0, pB1, u, NT - 1, wid, r32, hi, biasL); partialSM(pB0, pB1, m_reg, mnB, alB);
;   __syncthreads(); RESC(alB);
;   finishSM(pB0, pB1, alB, l_reg, pa0, pa1, pa2, pa3); SBAR();
;   pv_d0(o, vb0 + (int)SHM_V, pa0, pa1, pa2, pa3);
.Lda_skipl_3:
	s_add_u32 s31, s31, 1
	s_cmp_lt_u32 s31, 132
	s_cbranch_scc0 .Lda_skipk_3
	ds_read_b128 v[150:153], v204 offset:0
	ds_read_b128 v[154:157], v204 offset:8192
	ds_read_b128 v[158:161], v205 offset:0
	ds_read_b128 v[162:165], v205 offset:8192
	ds_read_b128 v[228:231], v206 offset:0
	ds_read_b128 v[232:235], v206 offset:8192
	ds_read_b128 v[236:239], v207 offset:0
	ds_read_b128 v[240:243], v207 offset:8192
.Lda_skipk_3:
	s_barrier
	s_cmp_lt_u32 s31, 132
	s_cbranch_scc1 .Lda_loop
	ds_read_b64_tr_b16 v[150:151], v196 offset:49152
	ds_read_b64_tr_b16 v[152:153], v196 offset:51200
	ds_read_b64_tr_b16 v[154:155], v196 offset:53248
	ds_read_b64_tr_b16 v[156:157], v196 offset:55296
	ds_read_b64_tr_b16 v[158:159], v196 offset:57344
	ds_read_b64_tr_b16 v[160:161], v196 offset:59392
	ds_read_b64_tr_b16 v[162:163], v196 offset:61440
	ds_read_b64_tr_b16 v[164:165], v196 offset:63488
	ds_read_b64_tr_b16 v[228:229], v196 offset:49664
	ds_read_b64_tr_b16 v[230:231], v196 offset:51712
	ds_read_b64_tr_b16 v[232:233], v196 offset:53760
	ds_read_b64_tr_b16 v[234:235], v196 offset:55808
	ds_read_b64_tr_b16 v[236:237], v196 offset:57856
	ds_read_b64_tr_b16 v[238:239], v196 offset:59904
	s_waitcnt lgkmcnt(12)
	v_mfma_f32_32x32x16_bf16 v[0:15], v[166:169], v[150:153], v[0:15]
	ds_read_b64_tr_b16 v[240:241], v196 offset:61952
	ds_read_b64_tr_b16 v[242:243], v196 offset:64000
	s_waitcnt lgkmcnt(12)
	v_mfma_f32_32x32x16_bf16 v[0:15], v[170:173], v[154:157], v[0:15]
	ds_read_b64_tr_b16 v[150:151], v196 offset:50176
	ds_read_b64_tr_b16 v[152:153], v196 offset:52224
	s_waitcnt lgkmcnt(12)
	v_mfma_f32_32x32x16_bf16 v[0:15], v[176:179], v[158:161], v[0:15]
	ds_read_b64_tr_b16 v[154:155], v196 offset:54272
	ds_read_b64_tr_b16 v[156:157], v196 offset:56320
	s_waitcnt lgkmcnt(12)
	v_mfma_f32_32x32x16_bf16 v[0:15], v[180:183], v[162:165], v[0:15]
	ds_read_b64_tr_b16 v[158:159], v196 offset:58368
	ds_read_b64_tr_b16 v[160:161], v196 offset:60416
	s_waitcnt lgkmcnt(12)
	v_mfma_f32_32x32x16_bf16 v[48:63], v[166:169], v[228:231], v[48:63]
	ds_read_b64_tr_b16 v[162:163], v196 offset:62464
	ds_read_b64_tr_b16 v[164:165], v196 offset:64512
	s_waitcnt lgkmcnt(12)
	v_mfma_f32_32x32x16_bf16 v[48:63], v[170:173], v[232:235], v[48:63]
	ds_read_b64_tr_b16 v[228:229], v196 offset:50688
	ds_read_b64_tr_b16 v[230:231], v196 offset:52736
	s_waitcnt lgkmcnt(12)
	v_mfma_f32_32x32x16_bf16 v[48:63], v[176:179], v[236:239], v[48:63]
	ds_read_b64_tr_b16 v[232:233], v196 offset:54784
	ds_read_b64_tr_b16 v[234:235], v196 offset:56832
	s_waitcnt lgkmcnt(12)
	v_mfma_f32_32x32x16_bf16 v[48:63], v[180:183], v[240:243], v[48:63]
	ds_read_b64_tr_b16 v[236:237], v196 offset:58880
	ds_read_b64_tr_b16 v[238:239], v196 offset:60928
	s_waitcnt lgkmcnt(12)
	v_mfma_f32_32x32x16_bf16 v[32:47], v[166:169], v[150:153], v[32:47]
	ds_read_b64_tr_b16 v[240:241], v196 offset:62976
	ds_read_b64_tr_b16 v[242:243], v196 offset:65024
	s_waitcnt lgkmcnt(12)
	v_mfma_f32_32x32x16_bf16 v[32:47], v[170:173], v[154:157], v[32:47]
	s_waitcnt lgkmcnt(10)
	v_mfma_f32_32x32x16_bf16 v[32:47], v[176:179], v[158:161], v[32:47]
	s_waitcnt lgkmcnt(8)
	v_mfma_f32_32x32x16_bf16 v[32:47], v[180:183], v[162:165], v[32:47]
	s_waitcnt lgkmcnt(6)
	v_mfma_f32_32x32x16_bf16 v[16:31], v[166:169], v[228:231], v[16:31]
	s_waitcnt lgkmcnt(4)
	v_mfma_f32_32x32x16_bf16 v[16:31], v[170:173], v[232:235], v[16:31]
	s_waitcnt lgkmcnt(2)
	v_mfma_f32_32x32x16_bf16 v[16:31], v[176:179], v[236:239], v[16:31]
	s_waitcnt lgkmcnt(0)
	v_mfma_f32_32x32x16_bf16 v[16:31], v[180:183], v[240:243], v[16:31]
	s_nop 12
	s_cmp_lt_u32 s36, 4
	s_cbranch_scc0 .Lda_trail
	s_barrier
